# GEMM tile start: the 128 accumulator VGPRs are zeroed with 64 v_mov_b64 instead of 127 v_mov_b32 (10 sites)
# speedup vs baseline: 1.0405x; 1.0002x over previous
.LBB0_204:
	s_ashr_i32 s15, s14, 31
	s_lshl_b64 s[16:17], s[14:15], 19
	v_readlane_b32 s11, v254, 8
	s_add_u32 s16, s11, s16
	v_readlane_b32 s11, v254, 9
	s_addc_u32 s17, s11, s17
	s_and_b64 s[18:19], s[4:5], exec
	s_cselect_b32 s15, s17, s23
	s_cselect_b32 s37, s16, s22
	s_ashr_i32 s11, s10, 31
	s_lshl_b64 s[18:19], s[10:11], 19
	v_readlane_b32 s11, v254, 51
	s_add_u32 s18, s11, s18
	v_readlane_b32 s11, v254, 52
	s_addc_u32 s19, s11, s19
	s_and_b64 s[24:25], s[4:5], exec
	s_cselect_b32 s11, s19, s21
	s_cselect_b32 s40, s18, s20
	s_add_u32 s41, s20, 0x100
	s_addc_u32 s72, s21, 0
	s_add_u32 s20, s22, 0x40080
	v_mov_b32_e32 v2, 0
	s_addc_u32 s21, s23, 0
	s_mov_b32 s73, -2
	v_mov_b32_e32 v3, v2
	v_mov_b64_e32 v[4:5], v[2:3]
	v_mov_b64_e32 v[6:7], v[2:3]
	v_mov_b64_e32 v[8:9], v[2:3]
	v_mov_b64_e32 v[10:11], v[2:3]
	v_mov_b64_e32 v[12:13], v[2:3]
	v_mov_b64_e32 v[14:15], v[2:3]
	v_mov_b64_e32 v[16:17], v[2:3]
	v_mov_b64_e32 v[18:19], v[2:3]
	v_mov_b64_e32 v[20:21], v[2:3]
	v_mov_b64_e32 v[22:23], v[2:3]
	v_mov_b64_e32 v[24:25], v[2:3]
	v_mov_b64_e32 v[26:27], v[2:3]
	v_mov_b64_e32 v[28:29], v[2:3]
	v_mov_b64_e32 v[30:31], v[2:3]
	v_mov_b64_e32 v[32:33], v[2:3]
	v_mov_b64_e32 v[34:35], v[2:3]
	v_mov_b64_e32 v[36:37], v[2:3]
	v_mov_b64_e32 v[38:39], v[2:3]
	v_mov_b64_e32 v[40:41], v[2:3]
	v_mov_b64_e32 v[42:43], v[2:3]
	v_mov_b64_e32 v[44:45], v[2:3]
	v_mov_b64_e32 v[46:47], v[2:3]
	v_mov_b64_e32 v[48:49], v[2:3]
	v_mov_b64_e32 v[50:51], v[2:3]
	v_mov_b64_e32 v[52:53], v[2:3]
	v_mov_b64_e32 v[54:55], v[2:3]
	v_mov_b64_e32 v[56:57], v[2:3]
	v_mov_b64_e32 v[58:59], v[2:3]
	v_mov_b64_e32 v[60:61], v[2:3]
	v_mov_b64_e32 v[62:63], v[2:3]
	v_mov_b64_e32 v[64:65], v[2:3]
	v_mov_b64_e32 v[66:67], v[2:3]
	v_mov_b64_e32 v[68:69], v[2:3]
	v_mov_b64_e32 v[70:71], v[2:3]
	v_mov_b64_e32 v[72:73], v[2:3]
	v_mov_b64_e32 v[74:75], v[2:3]
	v_mov_b64_e32 v[76:77], v[2:3]
	v_mov_b64_e32 v[78:79], v[2:3]
	v_mov_b64_e32 v[80:81], v[2:3]
	v_mov_b64_e32 v[82:83], v[2:3]
	v_mov_b64_e32 v[84:85], v[2:3]
	v_mov_b64_e32 v[86:87], v[2:3]
	v_mov_b64_e32 v[88:89], v[2:3]
	v_mov_b64_e32 v[90:91], v[2:3]
	v_mov_b64_e32 v[92:93], v[2:3]
	v_mov_b64_e32 v[94:95], v[2:3]
	v_mov_b64_e32 v[96:97], v[2:3]
	v_mov_b64_e32 v[98:99], v[2:3]
	v_mov_b64_e32 v[100:101], v[2:3]
	v_mov_b64_e32 v[102:103], v[2:3]
	v_mov_b64_e32 v[104:105], v[2:3]
	v_mov_b64_e32 v[106:107], v[2:3]
	v_mov_b64_e32 v[108:109], v[2:3]
	v_mov_b64_e32 v[110:111], v[2:3]
	v_mov_b64_e32 v[112:113], v[2:3]
	v_mov_b64_e32 v[114:115], v[2:3]
	v_mov_b64_e32 v[116:117], v[2:3]
	v_mov_b64_e32 v[118:119], v[2:3]
	v_mov_b64_e32 v[120:121], v[2:3]
	v_mov_b64_e32 v[122:123], v[2:3]
	v_mov_b64_e32 v[124:125], v[2:3]
	v_mov_b64_e32 v[126:127], v[2:3]
	v_mov_b64_e32 v[128:129], v[2:3]

.LBB0_607:
	v_lshl_add_u64 v[8:9], s[4:5], 0, v[0:1]
	v_mov_b32_e32 v133, v1
	v_readlane_b32 s10, v253, 58
	v_and_b32_e32 v220, 15, v216
	v_writelane_b32 v255, s8, 7
	s_lshl_b32 s6, s36, 6
	v_and_b32_e32 v16, 48, v216
	v_lshlrev_b32_e32 v17, 2, v216
	v_lshl_add_u64 v[10:11], s[4:5], 0, v[132:133]
	v_mov_b32_e32 v137, v1
	v_readlane_b32 s11, v253, 59
	s_and_b32 s7, s8, 3
	v_writelane_b32 v255, s6, 8
	v_or_b32_e32 v130, s6, v220
	s_lshl_b32 s6, s36, 13
	v_lshl_or_b32 v16, v220, 6, v16
	v_and_b32_e32 v17, 32, v17
	s_add_i32 m0, s71, 0x18000
	v_lshl_add_u64 v[8:9], v[8:9], 0, s[50:51]
	v_lshl_add_u64 v[12:13], s[10:11], 0, v[136:137]
	v_mov_b32_e32 v135, v1
	v_bitop3_b32 v18, v16, s6, v17 bitop3:0xde
	s_lshl_b32 s6, s7, 12
	s_waitcnt vmcnt(2)
	s_barrier
	global_load_lds_dwordx4 v[8:9], off
	v_lshl_add_u64 v[8:9], v[10:11], 0, s[50:51]
	s_add_i32 m0, s71, 0x1a000
	s_add_i32 s15, s71, 0x8000
	s_add_i32 s12, s71, 0xa000
	v_lshl_add_u64 v[14:15], s[10:11], 0, v[134:135]
	v_bitop3_b32 v131, v16, s6, v17 bitop3:0xde
	global_load_lds_dwordx4 v[8:9], off
	v_lshl_add_u64 v[8:9], v[12:13], 0, s[50:51]
	s_mov_b32 m0, s15
	s_add_u32 s6, s4, 0x40080
	v_writelane_b32 v255, s7, 9
	global_load_lds_dwordx4 v[8:9], off
	v_lshl_add_u64 v[8:9], v[14:15], 0, s[50:51]
	s_mov_b32 m0, s12
	s_addc_u32 s7, s5, 0
	global_load_lds_dwordx4 v[8:9], off
	s_add_i32 m0, s71, 0x1c000
	v_lshl_add_u64 v[8:9], s[6:7], 0, v[0:1]
	global_load_lds_dwordx4 v[8:9], off
	v_lshl_add_u64 v[8:9], s[6:7], 0, v[132:133]
	s_add_i32 m0, s71, 0x1e000
	v_readlane_b32 s6, v254, 40
	global_load_lds_dwordx4 v[8:9], off
	v_lshlrev_b32_e32 v8, 14, v2
	v_and_b32_e32 v8, 0xffff8000, v8
	v_lshl_add_u32 v3, v3, 11, v8
	v_and_b32_e32 v2, 1, v2
	v_lshl_or_b32 v2, v2, 6, v3
	v_lshl_add_u32 v138, v4, 1, v2
	v_lshlrev_b32_e32 v2, 14, v6
	v_and_b32_e32 v2, 0xffff8000, v2
	v_lshl_add_u32 v2, v5, 11, v2
	v_and_b32_e32 v3, 1, v6
	s_waitcnt vmcnt(6)
	v_lshl_or_b32 v2, v3, 6, v2
	v_lshl_add_u32 v140, v7, 1, v2
	v_mov_b32_e32 v2, 0
	s_mov_b32 s18, s6
	v_readlane_b32 s6, v253, 62
	v_mov_b32_e32 v139, v1
	v_mov_b32_e32 v141, v1
	s_mov_b32 s21, 0
	v_add_u32_e32 v146, 0, v18
	s_mov_b32 s20, s6
	v_mov_b32_e32 v3, v2
	v_mov_b64_e32 v[4:5], v[2:3]
	v_mov_b64_e32 v[6:7], v[2:3]
	v_mov_b64_e32 v[8:9], v[2:3]
	v_mov_b64_e32 v[10:11], v[2:3]
	v_mov_b64_e32 v[12:13], v[2:3]
	v_mov_b64_e32 v[14:15], v[2:3]
	v_mov_b64_e32 v[16:17], v[2:3]
	v_mov_b64_e32 v[18:19], v[2:3]
	v_mov_b64_e32 v[20:21], v[2:3]
	v_mov_b64_e32 v[22:23], v[2:3]
	v_mov_b64_e32 v[24:25], v[2:3]
	v_mov_b64_e32 v[26:27], v[2:3]
	v_mov_b64_e32 v[28:29], v[2:3]
	v_mov_b64_e32 v[30:31], v[2:3]
	v_mov_b64_e32 v[32:33], v[2:3]
	v_mov_b64_e32 v[34:35], v[2:3]
	v_mov_b64_e32 v[36:37], v[2:3]
	v_mov_b64_e32 v[38:39], v[2:3]
	v_mov_b64_e32 v[40:41], v[2:3]
	v_mov_b64_e32 v[42:43], v[2:3]
	v_mov_b64_e32 v[44:45], v[2:3]
	v_mov_b64_e32 v[46:47], v[2:3]
	v_mov_b64_e32 v[48:49], v[2:3]
	v_mov_b64_e32 v[50:51], v[2:3]
	v_mov_b64_e32 v[52:53], v[2:3]
	v_mov_b64_e32 v[54:55], v[2:3]
	v_mov_b64_e32 v[56:57], v[2:3]
	v_mov_b64_e32 v[58:59], v[2:3]
	v_mov_b64_e32 v[60:61], v[2:3]
	v_mov_b64_e32 v[62:63], v[2:3]
	v_mov_b64_e32 v[64:65], v[2:3]
	v_mov_b64_e32 v[66:67], v[2:3]
	v_mov_b64_e32 v[68:69], v[2:3]
	v_mov_b64_e32 v[70:71], v[2:3]
	v_mov_b64_e32 v[72:73], v[2:3]
	v_mov_b64_e32 v[74:75], v[2:3]
	v_mov_b64_e32 v[76:77], v[2:3]
	v_mov_b64_e32 v[78:79], v[2:3]
	v_mov_b64_e32 v[80:81], v[2:3]
	v_mov_b64_e32 v[82:83], v[2:3]
	v_mov_b64_e32 v[84:85], v[2:3]
	v_mov_b64_e32 v[86:87], v[2:3]
	v_mov_b64_e32 v[88:89], v[2:3]
	v_mov_b64_e32 v[90:91], v[2:3]
	v_mov_b64_e32 v[92:93], v[2:3]
	v_mov_b64_e32 v[94:95], v[2:3]
	v_mov_b64_e32 v[96:97], v[2:3]
	v_mov_b64_e32 v[98:99], v[2:3]
	v_mov_b64_e32 v[100:101], v[2:3]
	v_mov_b64_e32 v[102:103], v[2:3]
	v_mov_b64_e32 v[104:105], v[2:3]
	v_mov_b64_e32 v[106:107], v[2:3]
	v_mov_b64_e32 v[108:109], v[2:3]
	v_mov_b64_e32 v[110:111], v[2:3]
	v_mov_b64_e32 v[112:113], v[2:3]
	v_mov_b64_e32 v[114:115], v[2:3]
	v_mov_b64_e32 v[116:117], v[2:3]
	v_mov_b64_e32 v[118:119], v[2:3]
	v_mov_b64_e32 v[120:121], v[2:3]
	v_mov_b64_e32 v[122:123], v[2:3]
	v_mov_b64_e32 v[124:125], v[2:3]
	v_mov_b64_e32 v[126:127], v[2:3]
	v_mov_b64_e32 v[128:129], v[2:3]
	s_barrier
	v_readlane_b32 s7, v253, 63

.LBB0_615:
	s_add_u32 s4, s10, s30
	s_addc_u32 s5, s11, s31
	s_add_u32 s4, s4, 0x100
	s_addc_u32 s5, s5, 0
	s_add_u32 s74, s17, s30
	s_addc_u32 s75, vcc_lo, s31
	s_add_i32 s76, 0, 0x10000
	s_cmpk_eq_i32 s30, 0x700
	s_cselect_b32 s35, s25, s5
	s_cselect_b32 s34, vcc_hi, s4
	v_add_u32_e32 v147, s76, v131
	s_cselect_b32 s5, s23, s75
	s_cselect_b32 s4, s72, s74
	s_add_i32 s77, 0, 0x14000
	ds_read_b128 v[148:151], v147
	ds_read_b128 v[152:155], v147 offset:1024
	ds_read_b128 v[156:159], v147 offset:2048
	ds_read_b128 v[160:163], v147 offset:3072
	v_add_u32_e32 v147, s77, v131
	ds_read_b128 v[164:167], v147
	ds_read_b128 v[168:171], v147 offset:1024
	ds_read_b128 v[172:175], v147 offset:2048
	ds_read_b128 v[176:179], v147 offset:3072
	v_lshl_add_u64 v[208:209], v[144:145], 0, s[30:31]
	s_add_i32 m0, s71, 0xc000
	ds_read_b128 v[180:183], v146
	ds_read_b128 v[184:187], v146 offset:1024
	ds_read_b128 v[188:191], v146 offset:2048
	ds_read_b128 v[192:195], v146 offset:3072
	ds_read_b128 v[196:199], v146 offset:4096
	ds_read_b128 v[200:203], v146 offset:5120
	ds_read_b128 v[204:207], v146 offset:6144
	ds_read_b128 v[248:251], v146 offset:7168
	global_load_lds_dwordx4 v[208:209], off
	v_lshl_add_u64 v[208:209], v[142:143], 0, s[30:31]
	s_add_i32 m0, s71, 0xe000
	s_nop 0
	global_load_lds_dwordx4 v[208:209], off
	s_waitcnt vmcnt(8)
	s_waitcnt lgkmcnt(0)
	s_barrier
	s_setprio 1
	s_waitcnt lgkmcnt(0)
	v_mfma_f32_16x16x32_bf16 v[126:129], v[148:151], v[180:183], v[126:129]
	v_mfma_f32_16x16x32_bf16 v[122:125], v[156:159], v[180:183], v[122:125]
	v_mfma_f32_16x16x32_bf16 v[114:117], v[148:151], v[188:191], v[114:117]
	v_mfma_f32_16x16x32_bf16 v[106:109], v[156:159], v[188:191], v[106:109]
	v_mfma_f32_16x16x32_bf16 v[98:101], v[148:151], v[196:199], v[98:101]
	v_mfma_f32_16x16x32_bf16 v[90:93], v[156:159], v[196:199], v[90:93]
	v_mfma_f32_16x16x32_bf16 v[82:85], v[148:151], v[204:207], v[82:85]
	v_mfma_f32_16x16x32_bf16 v[74:77], v[156:159], v[204:207], v[74:77]
	v_mfma_f32_16x16x32_bf16 v[126:129], v[152:155], v[184:187], v[126:129]
	v_mfma_f32_16x16x32_bf16 v[122:125], v[160:163], v[184:187], v[122:125]
	v_mfma_f32_16x16x32_bf16 v[114:117], v[152:155], v[192:195], v[114:117]
	v_mfma_f32_16x16x32_bf16 v[106:109], v[160:163], v[192:195], v[106:109]
	v_mfma_f32_16x16x32_bf16 v[98:101], v[152:155], v[200:203], v[98:101]
	v_mfma_f32_16x16x32_bf16 v[90:93], v[160:163], v[200:203], v[90:93]
	v_mfma_f32_16x16x32_bf16 v[82:85], v[152:155], v[248:251], v[82:85]
	v_mfma_f32_16x16x32_bf16 v[74:77], v[160:163], v[248:251], v[74:77]
	s_setprio 0
	s_setprio 1
	v_mfma_f32_16x16x32_bf16 v[118:121], v[164:167], v[180:183], v[118:121]
	v_mfma_f32_16x16x32_bf16 v[110:113], v[172:175], v[180:183], v[110:113]
	v_mfma_f32_16x16x32_bf16 v[102:105], v[164:167], v[188:191], v[102:105]
	v_mfma_f32_16x16x32_bf16 v[94:97], v[172:175], v[188:191], v[94:97]
	v_mfma_f32_16x16x32_bf16 v[86:89], v[164:167], v[196:199], v[86:89]
	v_mfma_f32_16x16x32_bf16 v[78:81], v[172:175], v[196:199], v[78:81]
	v_mfma_f32_16x16x32_bf16 v[70:73], v[164:167], v[204:207], v[70:73]
	v_mfma_f32_16x16x32_bf16 v[66:69], v[172:175], v[204:207], v[66:69]
	v_mfma_f32_16x16x32_bf16 v[118:121], v[168:171], v[184:187], v[118:121]
	v_mfma_f32_16x16x32_bf16 v[110:113], v[176:179], v[184:187], v[110:113]
	v_mfma_f32_16x16x32_bf16 v[102:105], v[168:171], v[192:195], v[102:105]
	v_mfma_f32_16x16x32_bf16 v[94:97], v[176:179], v[192:195], v[94:97]
	v_mfma_f32_16x16x32_bf16 v[86:89], v[168:171], v[200:203], v[86:89]
	v_mfma_f32_16x16x32_bf16 v[78:81], v[176:179], v[200:203], v[78:81]
	v_mfma_f32_16x16x32_bf16 v[70:73], v[168:171], v[248:251], v[70:73]
	v_mfma_f32_16x16x32_bf16 v[66:69], v[176:179], v[248:251], v[66:69]
	s_setprio 0
	s_barrier
	s_add_i32 s74, s76, s38
	v_lshl_add_u64 v[208:209], s[4:5], 0, v[0:1]
	s_mov_b32 m0, s74
	ds_read_b128 v[180:183], v146 offset:16384
	ds_read_b128 v[184:187], v146 offset:17408
	ds_read_b128 v[188:191], v146 offset:18432
	ds_read_b128 v[192:195], v146 offset:19456
	ds_read_b128 v[196:199], v146 offset:20480
	ds_read_b128 v[200:203], v146 offset:21504
	ds_read_b128 v[204:207], v146 offset:22528
	ds_read_b128 v[248:251], v146 offset:23552
	global_load_lds_dwordx4 v[208:209], off
	s_add_i32 m0, s74, 0x2000
	s_add_u32 s74, s4, 0x40000
	v_lshl_add_u64 v[214:215], s[4:5], 0, v[132:133]
	s_addc_u32 s75, s5, 0
	s_add_i32 s76, s77, s38
	global_load_lds_dwordx4 v[214:215], off
	v_lshl_add_u64 v[218:219], s[74:75], 0, v[0:1]
	s_mov_b32 m0, s76
	v_lshl_add_u64 v[230:231], s[34:35], 0, v[134:135]
	global_load_lds_dwordx4 v[218:219], off
	v_lshl_add_u64 v[218:219], s[74:75], 0, v[132:133]
	s_add_i32 m0, s76, 0x2000
	s_nop 0
	global_load_lds_dwordx4 v[218:219], off
	v_lshl_add_u64 v[218:219], s[34:35], 0, v[136:137]
	s_mov_b32 m0, s71
	s_nop 0
	global_load_lds_dwordx4 v[218:219], off
	s_mov_b32 m0, s39
	s_nop 0
	global_load_lds_dwordx4 v[230:231], off
	s_waitcnt vmcnt(8)
	s_waitcnt lgkmcnt(0)
	s_barrier
	s_setprio 1
	s_waitcnt lgkmcnt(0)
	v_mfma_f32_16x16x32_bf16 v[62:65], v[148:151], v[180:183], v[62:65]
	v_mfma_f32_16x16x32_bf16 v[58:61], v[156:159], v[180:183], v[58:61]
	v_mfma_f32_16x16x32_bf16 v[50:53], v[148:151], v[188:191], v[50:53]
	v_mfma_f32_16x16x32_bf16 v[42:45], v[156:159], v[188:191], v[42:45]
	v_mfma_f32_16x16x32_bf16 v[34:37], v[148:151], v[196:199], v[34:37]
	v_mfma_f32_16x16x32_bf16 v[26:29], v[156:159], v[196:199], v[26:29]
	v_mfma_f32_16x16x32_bf16 v[18:21], v[148:151], v[204:207], v[18:21]
	v_mfma_f32_16x16x32_bf16 v[10:13], v[156:159], v[204:207], v[10:13]
	v_mfma_f32_16x16x32_bf16 v[62:65], v[152:155], v[184:187], v[62:65]
	v_mfma_f32_16x16x32_bf16 v[58:61], v[160:163], v[184:187], v[58:61]
	v_mfma_f32_16x16x32_bf16 v[50:53], v[152:155], v[192:195], v[50:53]
	v_mfma_f32_16x16x32_bf16 v[42:45], v[160:163], v[192:195], v[42:45]
	v_mfma_f32_16x16x32_bf16 v[34:37], v[152:155], v[200:203], v[34:37]
	v_mfma_f32_16x16x32_bf16 v[26:29], v[160:163], v[200:203], v[26:29]
	v_mfma_f32_16x16x32_bf16 v[18:21], v[152:155], v[248:251], v[18:21]
	v_mfma_f32_16x16x32_bf16 v[10:13], v[160:163], v[248:251], v[10:13]
	s_setprio 0
	s_setprio 1
	v_mfma_f32_16x16x32_bf16 v[54:57], v[164:167], v[180:183], v[54:57]
	v_mfma_f32_16x16x32_bf16 v[46:49], v[172:175], v[180:183], v[46:49]
	v_mfma_f32_16x16x32_bf16 v[38:41], v[164:167], v[188:191], v[38:41]
	v_mfma_f32_16x16x32_bf16 v[30:33], v[172:175], v[188:191], v[30:33]
	v_mfma_f32_16x16x32_bf16 v[22:25], v[164:167], v[196:199], v[22:25]
	v_mfma_f32_16x16x32_bf16 v[14:17], v[172:175], v[196:199], v[14:17]
	v_mfma_f32_16x16x32_bf16 v[6:9], v[164:167], v[204:207], v[6:9]
	v_mfma_f32_16x16x32_bf16 v[2:5], v[172:175], v[204:207], v[2:5]
	v_mfma_f32_16x16x32_bf16 v[54:57], v[168:171], v[184:187], v[54:57]
	v_mfma_f32_16x16x32_bf16 v[46:49], v[176:179], v[184:187], v[46:49]
	v_mfma_f32_16x16x32_bf16 v[38:41], v[168:171], v[192:195], v[38:41]
	v_mfma_f32_16x16x32_bf16 v[30:33], v[176:179], v[192:195], v[30:33]
	v_mfma_f32_16x16x32_bf16 v[22:25], v[168:171], v[200:203], v[22:25]
	v_mfma_f32_16x16x32_bf16 v[14:17], v[176:179], v[200:203], v[14:17]
	v_mfma_f32_16x16x32_bf16 v[6:9], v[168:171], v[248:251], v[6:9]
	v_mfma_f32_16x16x32_bf16 v[2:5], v[176:179], v[248:251], v[2:5]
	s_setprio 0
	s_barrier
	s_add_i32 s74, 0, 0x18000
	v_add_u32_e32 v147, s74, v131
	s_add_i32 s75, 0, 0x1c000
	ds_read_b128 v[148:151], v147
	ds_read_b128 v[152:155], v147 offset:1024
	ds_read_b128 v[156:159], v147 offset:2048
	ds_read_b128 v[160:163], v147 offset:3072
	v_add_u32_e32 v147, s75, v131
	ds_read_b128 v[164:167], v147
	ds_read_b128 v[168:171], v147 offset:1024
	ds_read_b128 v[172:175], v147 offset:2048
	ds_read_b128 v[176:179], v147 offset:3072
	s_add_u32 s34, s34, 0x40000
	s_addc_u32 s35, s35, 0
	s_mov_b32 m0, s37
	v_lshl_add_u64 v[232:233], s[34:35], 0, v[136:137]
	ds_read_b128 v[180:183], v146 offset:32768
	ds_read_b128 v[184:187], v146 offset:33792
	ds_read_b128 v[188:191], v146 offset:34816
	ds_read_b128 v[192:195], v146 offset:35840
	ds_read_b128 v[196:199], v146 offset:36864
	ds_read_b128 v[200:203], v146 offset:37888
	ds_read_b128 v[204:207], v146 offset:38912
	ds_read_b128 v[248:251], v146 offset:39936
	global_load_lds_dwordx4 v[232:233], off
	v_lshl_add_u64 v[232:233], s[34:35], 0, v[134:135]
	s_mov_b32 m0, s14
	s_nop 0
	global_load_lds_dwordx4 v[232:233], off
	s_waitcnt vmcnt(8)
	s_waitcnt lgkmcnt(0)
	s_barrier
	s_setprio 1
	s_waitcnt lgkmcnt(0)
	v_mfma_f32_16x16x32_bf16 v[126:129], v[148:151], v[180:183], v[126:129]
	v_mfma_f32_16x16x32_bf16 v[122:125], v[156:159], v[180:183], v[122:125]
	v_mfma_f32_16x16x32_bf16 v[114:117], v[148:151], v[188:191], v[114:117]
	v_mfma_f32_16x16x32_bf16 v[106:109], v[156:159], v[188:191], v[106:109]
	v_mfma_f32_16x16x32_bf16 v[98:101], v[148:151], v[196:199], v[98:101]
	v_mfma_f32_16x16x32_bf16 v[90:93], v[156:159], v[196:199], v[90:93]
	v_mfma_f32_16x16x32_bf16 v[82:85], v[148:151], v[204:207], v[82:85]
	v_mfma_f32_16x16x32_bf16 v[74:77], v[156:159], v[204:207], v[74:77]
	v_mfma_f32_16x16x32_bf16 v[126:129], v[152:155], v[184:187], v[126:129]
	v_mfma_f32_16x16x32_bf16 v[122:125], v[160:163], v[184:187], v[122:125]
	v_mfma_f32_16x16x32_bf16 v[114:117], v[152:155], v[192:195], v[114:117]
	v_mfma_f32_16x16x32_bf16 v[106:109], v[160:163], v[192:195], v[106:109]
	v_mfma_f32_16x16x32_bf16 v[98:101], v[152:155], v[200:203], v[98:101]
	v_mfma_f32_16x16x32_bf16 v[90:93], v[160:163], v[200:203], v[90:93]
	v_mfma_f32_16x16x32_bf16 v[82:85], v[152:155], v[248:251], v[82:85]
	v_mfma_f32_16x16x32_bf16 v[74:77], v[160:163], v[248:251], v[74:77]
	s_setprio 0
	s_setprio 1
	v_mfma_f32_16x16x32_bf16 v[118:121], v[164:167], v[180:183], v[118:121]
	v_mfma_f32_16x16x32_bf16 v[110:113], v[172:175], v[180:183], v[110:113]
	v_mfma_f32_16x16x32_bf16 v[102:105], v[164:167], v[188:191], v[102:105]
	v_mfma_f32_16x16x32_bf16 v[94:97], v[172:175], v[188:191], v[94:97]
	v_mfma_f32_16x16x32_bf16 v[86:89], v[164:167], v[196:199], v[86:89]
	v_mfma_f32_16x16x32_bf16 v[78:81], v[172:175], v[196:199], v[78:81]
	v_mfma_f32_16x16x32_bf16 v[70:73], v[164:167], v[204:207], v[70:73]
	v_mfma_f32_16x16x32_bf16 v[66:69], v[172:175], v[204:207], v[66:69]
	v_mfma_f32_16x16x32_bf16 v[118:121], v[168:171], v[184:187], v[118:121]
	v_mfma_f32_16x16x32_bf16 v[110:113], v[176:179], v[184:187], v[110:113]
	v_mfma_f32_16x16x32_bf16 v[102:105], v[168:171], v[192:195], v[102:105]
	v_mfma_f32_16x16x32_bf16 v[94:97], v[176:179], v[192:195], v[94:97]
	v_mfma_f32_16x16x32_bf16 v[86:89], v[168:171], v[200:203], v[86:89]
	v_mfma_f32_16x16x32_bf16 v[78:81], v[176:179], v[200:203], v[78:81]
	v_mfma_f32_16x16x32_bf16 v[70:73], v[168:171], v[248:251], v[70:73]
	v_mfma_f32_16x16x32_bf16 v[66:69], v[176:179], v[248:251], v[66:69]
	s_setprio 0
	s_barrier
	s_add_i32 s34, s74, s38
	v_lshl_add_u64 v[208:209], v[208:209], 0, s[50:51]
	s_mov_b32 m0, s34
	ds_read_b128 v[180:183], v146 offset:49152
	ds_read_b128 v[184:187], v146 offset:50176
	ds_read_b128 v[188:191], v146 offset:51200
	ds_read_b128 v[192:195], v146 offset:52224
	ds_read_b128 v[196:199], v146 offset:53248
	ds_read_b128 v[200:203], v146 offset:54272
	ds_read_b128 v[204:207], v146 offset:55296
	ds_read_b128 v[248:251], v146 offset:56320
	global_load_lds_dwordx4 v[208:209], off
	s_add_i32 m0, s34, 0x2000
	s_add_u32 s4, s4, 0x40080
	v_lshl_add_u64 v[208:209], v[214:215], 0, s[50:51]
	s_addc_u32 s5, s5, 0
	s_add_i32 s34, s75, s38
	global_load_lds_dwordx4 v[208:209], off
	v_lshl_add_u64 v[208:209], s[4:5], 0, v[0:1]
	s_mov_b32 m0, s34
	s_nop 0
	global_load_lds_dwordx4 v[208:209], off
	v_lshl_add_u64 v[208:209], s[4:5], 0, v[132:133]
	s_add_i32 m0, s34, 0x2000
	s_nop 0
	global_load_lds_dwordx4 v[208:209], off
	v_lshl_add_u64 v[208:209], v[218:219], 0, s[50:51]
	s_mov_b32 m0, s15
	s_nop 0
	global_load_lds_dwordx4 v[208:209], off
	v_lshl_add_u64 v[208:209], v[230:231], 0, s[50:51]
	s_mov_b32 m0, s12
	s_nop 0
	global_load_lds_dwordx4 v[208:209], off
	s_waitcnt vmcnt(8)
	s_waitcnt lgkmcnt(0)
	s_barrier
	s_setprio 1
	s_waitcnt lgkmcnt(0)
	v_mfma_f32_16x16x32_bf16 v[62:65], v[148:151], v[180:183], v[62:65]
	v_mfma_f32_16x16x32_bf16 v[58:61], v[156:159], v[180:183], v[58:61]
	v_mfma_f32_16x16x32_bf16 v[50:53], v[148:151], v[188:191], v[50:53]
	v_mfma_f32_16x16x32_bf16 v[42:45], v[156:159], v[188:191], v[42:45]
	v_mfma_f32_16x16x32_bf16 v[34:37], v[148:151], v[196:199], v[34:37]
	v_mfma_f32_16x16x32_bf16 v[26:29], v[156:159], v[196:199], v[26:29]
	v_mfma_f32_16x16x32_bf16 v[18:21], v[148:151], v[204:207], v[18:21]
	v_mfma_f32_16x16x32_bf16 v[10:13], v[156:159], v[204:207], v[10:13]
	v_mfma_f32_16x16x32_bf16 v[62:65], v[152:155], v[184:187], v[62:65]
	v_mfma_f32_16x16x32_bf16 v[58:61], v[160:163], v[184:187], v[58:61]
	v_mfma_f32_16x16x32_bf16 v[50:53], v[152:155], v[192:195], v[50:53]
	v_mfma_f32_16x16x32_bf16 v[42:45], v[160:163], v[192:195], v[42:45]
	v_mfma_f32_16x16x32_bf16 v[34:37], v[152:155], v[200:203], v[34:37]
	v_mfma_f32_16x16x32_bf16 v[26:29], v[160:163], v[200:203], v[26:29]
	v_mfma_f32_16x16x32_bf16 v[18:21], v[152:155], v[248:251], v[18:21]
	v_mfma_f32_16x16x32_bf16 v[10:13], v[160:163], v[248:251], v[10:13]
	s_setprio 0
	s_setprio 1
	v_mfma_f32_16x16x32_bf16 v[54:57], v[164:167], v[180:183], v[54:57]
	v_mfma_f32_16x16x32_bf16 v[46:49], v[172:175], v[180:183], v[46:49]
	v_mfma_f32_16x16x32_bf16 v[38:41], v[164:167], v[188:191], v[38:41]
	v_mfma_f32_16x16x32_bf16 v[30:33], v[172:175], v[188:191], v[30:33]
	v_mfma_f32_16x16x32_bf16 v[22:25], v[164:167], v[196:199], v[22:25]
	v_mfma_f32_16x16x32_bf16 v[14:17], v[172:175], v[196:199], v[14:17]
	v_mfma_f32_16x16x32_bf16 v[6:9], v[164:167], v[204:207], v[6:9]
	v_mfma_f32_16x16x32_bf16 v[2:5], v[172:175], v[204:207], v[2:5]
	v_mfma_f32_16x16x32_bf16 v[54:57], v[168:171], v[184:187], v[54:57]
	v_mfma_f32_16x16x32_bf16 v[46:49], v[176:179], v[184:187], v[46:49]
	v_mfma_f32_16x16x32_bf16 v[38:41], v[168:171], v[192:195], v[38:41]
	v_mfma_f32_16x16x32_bf16 v[30:33], v[176:179], v[192:195], v[30:33]
	v_mfma_f32_16x16x32_bf16 v[22:25], v[168:171], v[200:203], v[22:25]
	v_mfma_f32_16x16x32_bf16 v[14:17], v[176:179], v[200:203], v[14:17]
	v_mfma_f32_16x16x32_bf16 v[6:9], v[168:171], v[248:251], v[6:9]
	v_mfma_f32_16x16x32_bf16 v[2:5], v[176:179], v[248:251], v[2:5]
	s_setprio 0
	s_barrier
	s_add_i32 s73, s73, 2
	s_add_u32 s30, s30, 0x100
	s_addc_u32 s31, s31, 0
	s_cmp_gt_u32 s73, 13
	s_cbranch_scc0 .LBB0_615
	s_add_u32 s4, s17, 0xffffff00
	s_addc_u32 s5, vcc_lo, -1
	s_andn2_b64 vcc, exec, s[8:9]
	s_cbranch_vccnz .LBB0_618
	v_mov_b32_e32 v2, 0
	s_mov_b32 s18, s22
	s_mov_b32 s20, s24
	s_mov_b64 s[10:11], s[28:29]
	s_mov_b32 s21, s16
	v_mov_b32_e32 v3, v2
	v_mov_b64_e32 v[4:5], v[2:3]
	v_mov_b64_e32 v[6:7], v[2:3]
	v_mov_b64_e32 v[8:9], v[2:3]
	v_mov_b64_e32 v[10:11], v[2:3]
	v_mov_b64_e32 v[12:13], v[2:3]
	v_mov_b64_e32 v[14:15], v[2:3]
	v_mov_b64_e32 v[16:17], v[2:3]
	v_mov_b64_e32 v[18:19], v[2:3]
	v_mov_b64_e32 v[20:21], v[2:3]
	v_mov_b64_e32 v[22:23], v[2:3]
	v_mov_b64_e32 v[24:25], v[2:3]
	v_mov_b64_e32 v[26:27], v[2:3]
	v_mov_b64_e32 v[28:29], v[2:3]
	v_mov_b64_e32 v[30:31], v[2:3]
	v_mov_b64_e32 v[32:33], v[2:3]
	v_mov_b64_e32 v[34:35], v[2:3]
	v_mov_b64_e32 v[36:37], v[2:3]
	v_mov_b64_e32 v[38:39], v[2:3]
	v_mov_b64_e32 v[40:41], v[2:3]
	v_mov_b64_e32 v[42:43], v[2:3]
	v_mov_b64_e32 v[44:45], v[2:3]
	v_mov_b64_e32 v[46:47], v[2:3]
	v_mov_b64_e32 v[48:49], v[2:3]
	v_mov_b64_e32 v[50:51], v[2:3]
	v_mov_b64_e32 v[52:53], v[2:3]
	v_mov_b64_e32 v[54:55], v[2:3]
	v_mov_b64_e32 v[56:57], v[2:3]
	v_mov_b64_e32 v[58:59], v[2:3]
	v_mov_b64_e32 v[60:61], v[2:3]
	v_mov_b64_e32 v[62:63], v[2:3]
	v_mov_b64_e32 v[64:65], v[2:3]
	v_mov_b64_e32 v[66:67], v[2:3]
	v_mov_b64_e32 v[68:69], v[2:3]
	v_mov_b64_e32 v[70:71], v[2:3]
	v_mov_b64_e32 v[72:73], v[2:3]
	v_mov_b64_e32 v[74:75], v[2:3]
	v_mov_b64_e32 v[76:77], v[2:3]
	v_mov_b64_e32 v[78:79], v[2:3]
	v_mov_b64_e32 v[80:81], v[2:3]
	v_mov_b64_e32 v[82:83], v[2:3]
	v_mov_b64_e32 v[84:85], v[2:3]
	v_mov_b64_e32 v[86:87], v[2:3]
	v_mov_b64_e32 v[88:89], v[2:3]
	v_mov_b64_e32 v[90:91], v[2:3]
	v_mov_b64_e32 v[92:93], v[2:3]
	v_mov_b64_e32 v[94:95], v[2:3]
	v_mov_b64_e32 v[96:97], v[2:3]
	v_mov_b64_e32 v[98:99], v[2:3]
	v_mov_b64_e32 v[100:101], v[2:3]
	v_mov_b64_e32 v[102:103], v[2:3]
	v_mov_b64_e32 v[104:105], v[2:3]
	v_mov_b64_e32 v[106:107], v[2:3]
	v_mov_b64_e32 v[108:109], v[2:3]
	v_mov_b64_e32 v[110:111], v[2:3]
	v_mov_b64_e32 v[112:113], v[2:3]
	v_mov_b64_e32 v[114:115], v[2:3]
	v_mov_b64_e32 v[116:117], v[2:3]
	v_mov_b64_e32 v[118:119], v[2:3]
	v_mov_b64_e32 v[120:121], v[2:3]
	v_mov_b64_e32 v[122:123], v[2:3]
	v_mov_b64_e32 v[124:125], v[2:3]
	v_mov_b64_e32 v[126:127], v[2:3]
	v_mov_b64_e32 v[128:129], v[2:3]
	s_andn2_b64 vcc, exec, s[6:7]
	s_cbranch_vccnz .LBB0_619
	s_branch .LBB0_620

.LBB0_712:
	v_lshl_add_u64 v[8:9], s[4:5], 0, v[0:1]
	v_mov_b32_e32 v133, v1
	v_readlane_b32 s10, v253, 58
	v_writelane_b32 v255, s8, 7
	v_and_b32_e32 v247, 15, v216
	s_lshl_b32 s6, s12, 6
	v_and_b32_e32 v16, 48, v216
	v_lshlrev_b32_e32 v17, 2, v216
	v_lshl_add_u64 v[10:11], s[4:5], 0, v[132:133]
	v_mov_b32_e32 v137, v1
	v_readlane_b32 s11, v253, 59
	s_and_b32 s7, s8, 3
	v_writelane_b32 v255, s6, 8
	v_or_b32_e32 v130, s6, v247
	s_lshl_b32 s6, s12, 13
	v_lshl_or_b32 v16, v247, 6, v16
	v_and_b32_e32 v17, 32, v17
	s_add_i32 m0, s23, 0x18000
	v_lshl_add_u64 v[8:9], v[8:9], 0, s[50:51]
	v_lshl_add_u64 v[12:13], s[10:11], 0, v[136:137]
	v_mov_b32_e32 v135, v1
	v_bitop3_b32 v18, v16, s6, v17 bitop3:0xde
	s_lshl_b32 s6, s7, 12
	s_waitcnt vmcnt(2)
	s_barrier
	global_load_lds_dwordx4 v[8:9], off
	v_lshl_add_u64 v[8:9], v[10:11], 0, s[50:51]
	s_add_i32 m0, s23, 0x1a000
	s_add_i32 s15, s23, 0x8000
	s_add_i32 s71, s23, 0xa000
	v_lshl_add_u64 v[14:15], s[10:11], 0, v[134:135]
	v_bitop3_b32 v131, v16, s6, v17 bitop3:0xde
	global_load_lds_dwordx4 v[8:9], off
	v_lshl_add_u64 v[8:9], v[12:13], 0, s[50:51]
	s_mov_b32 m0, s15
	s_add_u32 s6, s4, 0x40080
	v_writelane_b32 v255, s7, 9
	global_load_lds_dwordx4 v[8:9], off
	v_lshl_add_u64 v[8:9], v[14:15], 0, s[50:51]
	s_mov_b32 m0, s71
	s_addc_u32 s7, s5, 0
	global_load_lds_dwordx4 v[8:9], off
	s_add_i32 m0, s23, 0x1c000
	v_lshl_add_u64 v[8:9], s[6:7], 0, v[0:1]
	global_load_lds_dwordx4 v[8:9], off
	v_lshl_add_u64 v[8:9], s[6:7], 0, v[132:133]
	s_add_i32 m0, s23, 0x1e000
	v_readlane_b32 s6, v254, 40
	global_load_lds_dwordx4 v[8:9], off
	v_lshlrev_b32_e32 v8, 14, v2
	v_and_b32_e32 v8, 0xffff8000, v8
	v_lshl_add_u32 v3, v3, 11, v8
	v_and_b32_e32 v2, 1, v2
	v_lshl_or_b32 v2, v2, 6, v3
	v_lshl_add_u32 v138, v4, 1, v2
	v_lshlrev_b32_e32 v2, 14, v6
	v_and_b32_e32 v2, 0xffff8000, v2
	v_lshl_add_u32 v2, v5, 11, v2
	v_and_b32_e32 v3, 1, v6
	s_waitcnt vmcnt(6)
	v_lshl_or_b32 v2, v3, 6, v2
	v_lshl_add_u32 v140, v7, 1, v2
	v_mov_b32_e32 v2, 0
	v_mov_b32_e32 v139, v1
	v_mov_b32_e32 v141, v1
	s_mov_b32 s16, 0
	v_add_u32_e32 v146, 0, v18
	s_mov_b32 s18, s6
	v_readlane_b32 s20, v253, 62
	v_mov_b32_e32 v3, v2
	v_mov_b64_e32 v[4:5], v[2:3]
	v_mov_b64_e32 v[6:7], v[2:3]
	v_mov_b64_e32 v[8:9], v[2:3]
	v_mov_b64_e32 v[10:11], v[2:3]
	v_mov_b64_e32 v[12:13], v[2:3]
	v_mov_b64_e32 v[14:15], v[2:3]
	v_mov_b64_e32 v[16:17], v[2:3]
	v_mov_b64_e32 v[18:19], v[2:3]
	v_mov_b64_e32 v[20:21], v[2:3]
	v_mov_b64_e32 v[22:23], v[2:3]
	v_mov_b64_e32 v[24:25], v[2:3]
	v_mov_b64_e32 v[26:27], v[2:3]
	v_mov_b64_e32 v[28:29], v[2:3]
	v_mov_b64_e32 v[30:31], v[2:3]
	v_mov_b64_e32 v[32:33], v[2:3]
	v_mov_b64_e32 v[34:35], v[2:3]
	v_mov_b64_e32 v[36:37], v[2:3]
	v_mov_b64_e32 v[38:39], v[2:3]
	v_mov_b64_e32 v[40:41], v[2:3]
	v_mov_b64_e32 v[42:43], v[2:3]
	v_mov_b64_e32 v[44:45], v[2:3]
	v_mov_b64_e32 v[46:47], v[2:3]
	v_mov_b64_e32 v[48:49], v[2:3]
	v_mov_b64_e32 v[50:51], v[2:3]
	v_mov_b64_e32 v[52:53], v[2:3]
	v_mov_b64_e32 v[54:55], v[2:3]
	v_mov_b64_e32 v[56:57], v[2:3]
	v_mov_b64_e32 v[58:59], v[2:3]
	v_mov_b64_e32 v[60:61], v[2:3]
	v_mov_b64_e32 v[62:63], v[2:3]
	v_mov_b64_e32 v[64:65], v[2:3]
	v_mov_b64_e32 v[66:67], v[2:3]
	v_mov_b64_e32 v[68:69], v[2:3]
	v_mov_b64_e32 v[70:71], v[2:3]
	v_mov_b64_e32 v[72:73], v[2:3]
	v_mov_b64_e32 v[74:75], v[2:3]
	v_mov_b64_e32 v[76:77], v[2:3]
	v_mov_b64_e32 v[78:79], v[2:3]
	v_mov_b64_e32 v[80:81], v[2:3]
	v_mov_b64_e32 v[82:83], v[2:3]
	v_mov_b64_e32 v[84:85], v[2:3]
	v_mov_b64_e32 v[86:87], v[2:3]
	v_mov_b64_e32 v[88:89], v[2:3]
	v_mov_b64_e32 v[90:91], v[2:3]
	v_mov_b64_e32 v[92:93], v[2:3]
	v_mov_b64_e32 v[94:95], v[2:3]
	v_mov_b64_e32 v[96:97], v[2:3]
	v_mov_b64_e32 v[98:99], v[2:3]
	v_mov_b64_e32 v[100:101], v[2:3]
	v_mov_b64_e32 v[102:103], v[2:3]
	v_mov_b64_e32 v[104:105], v[2:3]
	v_mov_b64_e32 v[106:107], v[2:3]
	v_mov_b64_e32 v[108:109], v[2:3]
	v_mov_b64_e32 v[110:111], v[2:3]
	v_mov_b64_e32 v[112:113], v[2:3]
	v_mov_b64_e32 v[114:115], v[2:3]
	v_mov_b64_e32 v[116:117], v[2:3]
	v_mov_b64_e32 v[118:119], v[2:3]
	v_mov_b64_e32 v[120:121], v[2:3]
	v_mov_b64_e32 v[122:123], v[2:3]
	v_mov_b64_e32 v[124:125], v[2:3]
	v_mov_b64_e32 v[126:127], v[2:3]
	v_mov_b64_e32 v[128:129], v[2:3]
	s_barrier
	v_readlane_b32 s21, v253, 63

.LBB0_720:
	s_add_u32 s4, s10, s34
	s_addc_u32 s5, s11, s35
	s_add_u32 s4, s4, 0x100
	s_addc_u32 s5, s5, 0
	s_add_u32 s74, s17, s34
	s_addc_u32 s75, vcc_lo, s35
	s_add_i32 s76, 0, 0x10000
	s_cmpk_eq_i32 s34, 0x700
	s_cselect_b32 s37, s27, s5
	s_cselect_b32 s36, vcc_hi, s4
	v_add_u32_e32 v147, s76, v131
	s_cselect_b32 s5, s25, s75
	s_cselect_b32 s4, s72, s74
	s_add_i32 s77, 0, 0x14000
	ds_read_b128 v[148:151], v147
	ds_read_b128 v[152:155], v147 offset:1024
	ds_read_b128 v[156:159], v147 offset:2048
	ds_read_b128 v[160:163], v147 offset:3072
	v_add_u32_e32 v147, s77, v131
	ds_read_b128 v[164:167], v147
	ds_read_b128 v[168:171], v147 offset:1024
	ds_read_b128 v[172:175], v147 offset:2048
	ds_read_b128 v[176:179], v147 offset:3072
	v_lshl_add_u64 v[208:209], v[144:145], 0, s[34:35]
	s_add_i32 m0, s23, 0xc000
	ds_read_b128 v[180:183], v146
	ds_read_b128 v[184:187], v146 offset:1024
	ds_read_b128 v[188:191], v146 offset:2048
	ds_read_b128 v[192:195], v146 offset:3072
	ds_read_b128 v[196:199], v146 offset:4096
	ds_read_b128 v[200:203], v146 offset:5120
	ds_read_b128 v[204:207], v146 offset:6144
	ds_read_b128 v[218:221], v146 offset:7168
	global_load_lds_dwordx4 v[208:209], off
	v_lshl_add_u64 v[208:209], v[142:143], 0, s[34:35]
	s_add_i32 m0, s23, 0xe000
	s_nop 0
	global_load_lds_dwordx4 v[208:209], off
	s_waitcnt vmcnt(8)
	s_waitcnt lgkmcnt(0)
	s_barrier
	s_setprio 1
	s_waitcnt lgkmcnt(0)
	v_mfma_f32_16x16x32_bf16 v[126:129], v[148:151], v[180:183], v[126:129]
	v_mfma_f32_16x16x32_bf16 v[122:125], v[156:159], v[180:183], v[122:125]
	v_mfma_f32_16x16x32_bf16 v[118:121], v[148:151], v[188:191], v[118:121]
	v_mfma_f32_16x16x32_bf16 v[110:113], v[156:159], v[188:191], v[110:113]
	v_mfma_f32_16x16x32_bf16 v[102:105], v[148:151], v[196:199], v[102:105]
	v_mfma_f32_16x16x32_bf16 v[94:97], v[156:159], v[196:199], v[94:97]
	v_mfma_f32_16x16x32_bf16 v[86:89], v[148:151], v[204:207], v[86:89]
	v_mfma_f32_16x16x32_bf16 v[78:81], v[156:159], v[204:207], v[78:81]
	v_mfma_f32_16x16x32_bf16 v[126:129], v[152:155], v[184:187], v[126:129]
	v_mfma_f32_16x16x32_bf16 v[122:125], v[160:163], v[184:187], v[122:125]
	v_mfma_f32_16x16x32_bf16 v[118:121], v[152:155], v[192:195], v[118:121]
	v_mfma_f32_16x16x32_bf16 v[110:113], v[160:163], v[192:195], v[110:113]
	v_mfma_f32_16x16x32_bf16 v[102:105], v[152:155], v[200:203], v[102:105]
	v_mfma_f32_16x16x32_bf16 v[94:97], v[160:163], v[200:203], v[94:97]
	v_mfma_f32_16x16x32_bf16 v[86:89], v[152:155], v[218:221], v[86:89]
	v_mfma_f32_16x16x32_bf16 v[78:81], v[160:163], v[218:221], v[78:81]
	s_setprio 0
	s_setprio 1
	v_mfma_f32_16x16x32_bf16 v[114:117], v[164:167], v[180:183], v[114:117]
	v_mfma_f32_16x16x32_bf16 v[106:109], v[172:175], v[180:183], v[106:109]
	v_mfma_f32_16x16x32_bf16 v[98:101], v[164:167], v[188:191], v[98:101]
	v_mfma_f32_16x16x32_bf16 v[90:93], v[172:175], v[188:191], v[90:93]
	v_mfma_f32_16x16x32_bf16 v[82:85], v[164:167], v[196:199], v[82:85]
	v_mfma_f32_16x16x32_bf16 v[74:77], v[172:175], v[196:199], v[74:77]
	v_mfma_f32_16x16x32_bf16 v[70:73], v[164:167], v[204:207], v[70:73]
	v_mfma_f32_16x16x32_bf16 v[66:69], v[172:175], v[204:207], v[66:69]
	v_mfma_f32_16x16x32_bf16 v[114:117], v[168:171], v[184:187], v[114:117]
	v_mfma_f32_16x16x32_bf16 v[106:109], v[176:179], v[184:187], v[106:109]
	v_mfma_f32_16x16x32_bf16 v[98:101], v[168:171], v[192:195], v[98:101]
	v_mfma_f32_16x16x32_bf16 v[90:93], v[176:179], v[192:195], v[90:93]
	v_mfma_f32_16x16x32_bf16 v[82:85], v[168:171], v[200:203], v[82:85]
	v_mfma_f32_16x16x32_bf16 v[74:77], v[176:179], v[200:203], v[74:77]
	v_mfma_f32_16x16x32_bf16 v[70:73], v[168:171], v[218:221], v[70:73]
	v_mfma_f32_16x16x32_bf16 v[66:69], v[176:179], v[218:221], v[66:69]
	s_setprio 0
	s_barrier
	s_add_i32 s74, s76, s22
	v_lshl_add_u64 v[208:209], s[4:5], 0, v[0:1]
	s_mov_b32 m0, s74
	ds_read_b128 v[180:183], v146 offset:16384
	ds_read_b128 v[184:187], v146 offset:17408
	ds_read_b128 v[188:191], v146 offset:18432
	ds_read_b128 v[192:195], v146 offset:19456
	ds_read_b128 v[196:199], v146 offset:20480
	ds_read_b128 v[200:203], v146 offset:21504
	ds_read_b128 v[204:207], v146 offset:22528
	ds_read_b128 v[218:221], v146 offset:23552
	global_load_lds_dwordx4 v[208:209], off
	s_add_i32 m0, s74, 0x2000
	s_add_u32 s74, s4, 0x40000
	v_lshl_add_u64 v[214:215], s[4:5], 0, v[132:133]
	s_addc_u32 s75, s5, 0
	s_add_i32 s76, s77, s22
	global_load_lds_dwordx4 v[214:215], off
	v_lshl_add_u64 v[230:231], s[74:75], 0, v[0:1]
	s_mov_b32 m0, s76
	v_lshl_add_u64 v[232:233], s[36:37], 0, v[134:135]
	global_load_lds_dwordx4 v[230:231], off
	v_lshl_add_u64 v[230:231], s[74:75], 0, v[132:133]
	s_add_i32 m0, s76, 0x2000
	s_nop 0
	global_load_lds_dwordx4 v[230:231], off
	v_lshl_add_u64 v[230:231], s[36:37], 0, v[136:137]
	s_mov_b32 m0, s23
	s_nop 0
	global_load_lds_dwordx4 v[230:231], off
	s_mov_b32 m0, s39
	s_nop 0
	global_load_lds_dwordx4 v[232:233], off
	s_waitcnt vmcnt(8)
	s_waitcnt lgkmcnt(0)
	s_barrier
	s_setprio 1
	s_waitcnt lgkmcnt(0)
	v_mfma_f32_16x16x32_bf16 v[62:65], v[148:151], v[180:183], v[62:65]
	v_mfma_f32_16x16x32_bf16 v[58:61], v[156:159], v[180:183], v[58:61]
	v_mfma_f32_16x16x32_bf16 v[46:49], v[148:151], v[188:191], v[46:49]
	v_mfma_f32_16x16x32_bf16 v[42:45], v[156:159], v[188:191], v[42:45]
	v_mfma_f32_16x16x32_bf16 v[30:33], v[148:151], v[196:199], v[30:33]
	v_mfma_f32_16x16x32_bf16 v[26:29], v[156:159], v[196:199], v[26:29]
	v_mfma_f32_16x16x32_bf16 v[14:17], v[148:151], v[204:207], v[14:17]
	v_mfma_f32_16x16x32_bf16 v[10:13], v[156:159], v[204:207], v[10:13]
	v_mfma_f32_16x16x32_bf16 v[62:65], v[152:155], v[184:187], v[62:65]
	v_mfma_f32_16x16x32_bf16 v[58:61], v[160:163], v[184:187], v[58:61]
	v_mfma_f32_16x16x32_bf16 v[46:49], v[152:155], v[192:195], v[46:49]
	v_mfma_f32_16x16x32_bf16 v[42:45], v[160:163], v[192:195], v[42:45]
	v_mfma_f32_16x16x32_bf16 v[30:33], v[152:155], v[200:203], v[30:33]
	v_mfma_f32_16x16x32_bf16 v[26:29], v[160:163], v[200:203], v[26:29]
	v_mfma_f32_16x16x32_bf16 v[14:17], v[152:155], v[218:221], v[14:17]
	v_mfma_f32_16x16x32_bf16 v[10:13], v[160:163], v[218:221], v[10:13]
	s_setprio 0
	s_setprio 1
	v_mfma_f32_16x16x32_bf16 v[54:57], v[164:167], v[180:183], v[54:57]
	v_mfma_f32_16x16x32_bf16 v[50:53], v[172:175], v[180:183], v[50:53]
	v_mfma_f32_16x16x32_bf16 v[38:41], v[164:167], v[188:191], v[38:41]
	v_mfma_f32_16x16x32_bf16 v[34:37], v[172:175], v[188:191], v[34:37]
	v_mfma_f32_16x16x32_bf16 v[22:25], v[164:167], v[196:199], v[22:25]
	v_mfma_f32_16x16x32_bf16 v[18:21], v[172:175], v[196:199], v[18:21]
	v_mfma_f32_16x16x32_bf16 v[6:9], v[164:167], v[204:207], v[6:9]
	v_mfma_f32_16x16x32_bf16 v[2:5], v[172:175], v[204:207], v[2:5]
	v_mfma_f32_16x16x32_bf16 v[54:57], v[168:171], v[184:187], v[54:57]
	v_mfma_f32_16x16x32_bf16 v[50:53], v[176:179], v[184:187], v[50:53]
	v_mfma_f32_16x16x32_bf16 v[38:41], v[168:171], v[192:195], v[38:41]
	v_mfma_f32_16x16x32_bf16 v[34:37], v[176:179], v[192:195], v[34:37]
	v_mfma_f32_16x16x32_bf16 v[22:25], v[168:171], v[200:203], v[22:25]
	v_mfma_f32_16x16x32_bf16 v[18:21], v[176:179], v[200:203], v[18:21]
	v_mfma_f32_16x16x32_bf16 v[6:9], v[168:171], v[218:221], v[6:9]
	v_mfma_f32_16x16x32_bf16 v[2:5], v[176:179], v[218:221], v[2:5]
	s_setprio 0
	s_barrier
	s_add_i32 s74, 0, 0x18000
	v_add_u32_e32 v147, s74, v131
	s_add_i32 s75, 0, 0x1c000
	ds_read_b128 v[148:151], v147
	ds_read_b128 v[152:155], v147 offset:1024
	ds_read_b128 v[156:159], v147 offset:2048
	ds_read_b128 v[160:163], v147 offset:3072
	v_add_u32_e32 v147, s75, v131
	ds_read_b128 v[164:167], v147
	ds_read_b128 v[168:171], v147 offset:1024
	ds_read_b128 v[172:175], v147 offset:2048
	ds_read_b128 v[176:179], v147 offset:3072
	s_add_u32 s36, s36, 0x40000
	s_addc_u32 s37, s37, 0
	s_mov_b32 m0, s38
	v_lshl_add_u64 v[234:235], s[36:37], 0, v[136:137]
	ds_read_b128 v[180:183], v146 offset:32768
	ds_read_b128 v[184:187], v146 offset:33792
	ds_read_b128 v[188:191], v146 offset:34816
	ds_read_b128 v[192:195], v146 offset:35840
	ds_read_b128 v[196:199], v146 offset:36864
	ds_read_b128 v[200:203], v146 offset:37888
	ds_read_b128 v[204:207], v146 offset:38912
	ds_read_b128 v[218:221], v146 offset:39936
	global_load_lds_dwordx4 v[234:235], off
	v_lshl_add_u64 v[234:235], s[36:37], 0, v[134:135]
	s_mov_b32 m0, s14
	s_nop 0
	global_load_lds_dwordx4 v[234:235], off
	s_waitcnt vmcnt(8)
	s_waitcnt lgkmcnt(0)
	s_barrier
	s_setprio 1
	s_waitcnt lgkmcnt(0)
	v_mfma_f32_16x16x32_bf16 v[126:129], v[148:151], v[180:183], v[126:129]
	v_mfma_f32_16x16x32_bf16 v[122:125], v[156:159], v[180:183], v[122:125]
	v_mfma_f32_16x16x32_bf16 v[118:121], v[148:151], v[188:191], v[118:121]
	v_mfma_f32_16x16x32_bf16 v[110:113], v[156:159], v[188:191], v[110:113]
	v_mfma_f32_16x16x32_bf16 v[102:105], v[148:151], v[196:199], v[102:105]
	v_mfma_f32_16x16x32_bf16 v[94:97], v[156:159], v[196:199], v[94:97]
	v_mfma_f32_16x16x32_bf16 v[86:89], v[148:151], v[204:207], v[86:89]
	v_mfma_f32_16x16x32_bf16 v[78:81], v[156:159], v[204:207], v[78:81]
	v_mfma_f32_16x16x32_bf16 v[126:129], v[152:155], v[184:187], v[126:129]
	v_mfma_f32_16x16x32_bf16 v[122:125], v[160:163], v[184:187], v[122:125]
	v_mfma_f32_16x16x32_bf16 v[118:121], v[152:155], v[192:195], v[118:121]
	v_mfma_f32_16x16x32_bf16 v[110:113], v[160:163], v[192:195], v[110:113]
	v_mfma_f32_16x16x32_bf16 v[102:105], v[152:155], v[200:203], v[102:105]
	v_mfma_f32_16x16x32_bf16 v[94:97], v[160:163], v[200:203], v[94:97]
	v_mfma_f32_16x16x32_bf16 v[86:89], v[152:155], v[218:221], v[86:89]
	v_mfma_f32_16x16x32_bf16 v[78:81], v[160:163], v[218:221], v[78:81]
	s_setprio 0
	s_setprio 1
	v_mfma_f32_16x16x32_bf16 v[114:117], v[164:167], v[180:183], v[114:117]
	v_mfma_f32_16x16x32_bf16 v[106:109], v[172:175], v[180:183], v[106:109]
	v_mfma_f32_16x16x32_bf16 v[98:101], v[164:167], v[188:191], v[98:101]
	v_mfma_f32_16x16x32_bf16 v[90:93], v[172:175], v[188:191], v[90:93]
	v_mfma_f32_16x16x32_bf16 v[82:85], v[164:167], v[196:199], v[82:85]
	v_mfma_f32_16x16x32_bf16 v[74:77], v[172:175], v[196:199], v[74:77]
	v_mfma_f32_16x16x32_bf16 v[70:73], v[164:167], v[204:207], v[70:73]
	v_mfma_f32_16x16x32_bf16 v[66:69], v[172:175], v[204:207], v[66:69]
	v_mfma_f32_16x16x32_bf16 v[114:117], v[168:171], v[184:187], v[114:117]
	v_mfma_f32_16x16x32_bf16 v[106:109], v[176:179], v[184:187], v[106:109]
	v_mfma_f32_16x16x32_bf16 v[98:101], v[168:171], v[192:195], v[98:101]
	v_mfma_f32_16x16x32_bf16 v[90:93], v[176:179], v[192:195], v[90:93]
	v_mfma_f32_16x16x32_bf16 v[82:85], v[168:171], v[200:203], v[82:85]
	v_mfma_f32_16x16x32_bf16 v[74:77], v[176:179], v[200:203], v[74:77]
	v_mfma_f32_16x16x32_bf16 v[70:73], v[168:171], v[218:221], v[70:73]
	v_mfma_f32_16x16x32_bf16 v[66:69], v[176:179], v[218:221], v[66:69]
	s_setprio 0
	s_barrier
	s_add_i32 s36, s74, s22
	v_lshl_add_u64 v[208:209], v[208:209], 0, s[50:51]
	s_mov_b32 m0, s36
	ds_read_b128 v[180:183], v146 offset:49152
	ds_read_b128 v[184:187], v146 offset:50176
	ds_read_b128 v[188:191], v146 offset:51200
	ds_read_b128 v[192:195], v146 offset:52224
	ds_read_b128 v[196:199], v146 offset:53248
	ds_read_b128 v[200:203], v146 offset:54272
	ds_read_b128 v[204:207], v146 offset:55296
	ds_read_b128 v[218:221], v146 offset:56320
	global_load_lds_dwordx4 v[208:209], off
	s_add_i32 m0, s36, 0x2000
	s_add_u32 s4, s4, 0x40080
	v_lshl_add_u64 v[208:209], v[214:215], 0, s[50:51]
	s_addc_u32 s5, s5, 0
	s_add_i32 s36, s75, s22
	global_load_lds_dwordx4 v[208:209], off
	v_lshl_add_u64 v[208:209], s[4:5], 0, v[0:1]
	s_mov_b32 m0, s36
	s_nop 0
	global_load_lds_dwordx4 v[208:209], off
	v_lshl_add_u64 v[208:209], s[4:5], 0, v[132:133]
	s_add_i32 m0, s36, 0x2000
	s_nop 0
	global_load_lds_dwordx4 v[208:209], off
	v_lshl_add_u64 v[208:209], v[230:231], 0, s[50:51]
	s_mov_b32 m0, s15
	s_nop 0
	global_load_lds_dwordx4 v[208:209], off
	v_lshl_add_u64 v[208:209], v[232:233], 0, s[50:51]
	s_mov_b32 m0, s71
	s_nop 0
	global_load_lds_dwordx4 v[208:209], off
	s_waitcnt vmcnt(8)
	s_waitcnt lgkmcnt(0)
	s_barrier
	s_setprio 1
	s_waitcnt lgkmcnt(0)
	v_mfma_f32_16x16x32_bf16 v[62:65], v[148:151], v[180:183], v[62:65]
	v_mfma_f32_16x16x32_bf16 v[58:61], v[156:159], v[180:183], v[58:61]
	v_mfma_f32_16x16x32_bf16 v[46:49], v[148:151], v[188:191], v[46:49]
	v_mfma_f32_16x16x32_bf16 v[42:45], v[156:159], v[188:191], v[42:45]
	v_mfma_f32_16x16x32_bf16 v[30:33], v[148:151], v[196:199], v[30:33]
	v_mfma_f32_16x16x32_bf16 v[26:29], v[156:159], v[196:199], v[26:29]
	v_mfma_f32_16x16x32_bf16 v[14:17], v[148:151], v[204:207], v[14:17]
	v_mfma_f32_16x16x32_bf16 v[10:13], v[156:159], v[204:207], v[10:13]
	v_mfma_f32_16x16x32_bf16 v[62:65], v[152:155], v[184:187], v[62:65]
	v_mfma_f32_16x16x32_bf16 v[58:61], v[160:163], v[184:187], v[58:61]
	v_mfma_f32_16x16x32_bf16 v[46:49], v[152:155], v[192:195], v[46:49]
	v_mfma_f32_16x16x32_bf16 v[42:45], v[160:163], v[192:195], v[42:45]
	v_mfma_f32_16x16x32_bf16 v[30:33], v[152:155], v[200:203], v[30:33]
	v_mfma_f32_16x16x32_bf16 v[26:29], v[160:163], v[200:203], v[26:29]
	v_mfma_f32_16x16x32_bf16 v[14:17], v[152:155], v[218:221], v[14:17]
	v_mfma_f32_16x16x32_bf16 v[10:13], v[160:163], v[218:221], v[10:13]
	s_setprio 0
	s_setprio 1
	v_mfma_f32_16x16x32_bf16 v[54:57], v[164:167], v[180:183], v[54:57]
	v_mfma_f32_16x16x32_bf16 v[50:53], v[172:175], v[180:183], v[50:53]
	v_mfma_f32_16x16x32_bf16 v[38:41], v[164:167], v[188:191], v[38:41]
	v_mfma_f32_16x16x32_bf16 v[34:37], v[172:175], v[188:191], v[34:37]
	v_mfma_f32_16x16x32_bf16 v[22:25], v[164:167], v[196:199], v[22:25]
	v_mfma_f32_16x16x32_bf16 v[18:21], v[172:175], v[196:199], v[18:21]
	v_mfma_f32_16x16x32_bf16 v[6:9], v[164:167], v[204:207], v[6:9]
	v_mfma_f32_16x16x32_bf16 v[2:5], v[172:175], v[204:207], v[2:5]
	v_mfma_f32_16x16x32_bf16 v[54:57], v[168:171], v[184:187], v[54:57]
	v_mfma_f32_16x16x32_bf16 v[50:53], v[176:179], v[184:187], v[50:53]
	v_mfma_f32_16x16x32_bf16 v[38:41], v[168:171], v[192:195], v[38:41]
	v_mfma_f32_16x16x32_bf16 v[34:37], v[176:179], v[192:195], v[34:37]
	v_mfma_f32_16x16x32_bf16 v[22:25], v[168:171], v[200:203], v[22:25]
	v_mfma_f32_16x16x32_bf16 v[18:21], v[176:179], v[200:203], v[18:21]
	v_mfma_f32_16x16x32_bf16 v[6:9], v[168:171], v[218:221], v[6:9]
	v_mfma_f32_16x16x32_bf16 v[2:5], v[176:179], v[218:221], v[2:5]
	s_setprio 0
	s_barrier
	s_add_i32 s73, s73, 2
	s_add_u32 s34, s34, 0x100
	s_addc_u32 s35, s35, 0
	s_cmp_gt_u32 s73, 13
	s_cbranch_scc0 .LBB0_720
	s_add_u32 s4, s17, 0xffffff00
	s_addc_u32 s5, vcc_lo, -1
	s_andn2_b64 vcc, exec, s[8:9]
	s_cbranch_vccnz .LBB0_723
	v_mov_b32_e32 v2, 0
	s_mov_b32 s18, s24
	s_mov_b32 s20, s26
	s_mov_b64 s[10:11], s[30:31]
	s_mov_b32 s16, s21
	v_mov_b32_e32 v3, v2
	v_mov_b64_e32 v[4:5], v[2:3]
	v_mov_b64_e32 v[6:7], v[2:3]
	v_mov_b64_e32 v[8:9], v[2:3]
	v_mov_b64_e32 v[10:11], v[2:3]
	v_mov_b64_e32 v[12:13], v[2:3]
	v_mov_b64_e32 v[14:15], v[2:3]
	v_mov_b64_e32 v[16:17], v[2:3]
	v_mov_b64_e32 v[18:19], v[2:3]
	v_mov_b64_e32 v[20:21], v[2:3]
	v_mov_b64_e32 v[22:23], v[2:3]
	v_mov_b64_e32 v[24:25], v[2:3]
	v_mov_b64_e32 v[26:27], v[2:3]
	v_mov_b64_e32 v[28:29], v[2:3]
	v_mov_b64_e32 v[30:31], v[2:3]
	v_mov_b64_e32 v[32:33], v[2:3]
	v_mov_b64_e32 v[34:35], v[2:3]
	v_mov_b64_e32 v[36:37], v[2:3]
	v_mov_b64_e32 v[38:39], v[2:3]
	v_mov_b64_e32 v[40:41], v[2:3]
	v_mov_b64_e32 v[42:43], v[2:3]
	v_mov_b64_e32 v[44:45], v[2:3]
	v_mov_b64_e32 v[46:47], v[2:3]
	v_mov_b64_e32 v[48:49], v[2:3]
	v_mov_b64_e32 v[50:51], v[2:3]
	v_mov_b64_e32 v[52:53], v[2:3]
	v_mov_b64_e32 v[54:55], v[2:3]
	v_mov_b64_e32 v[56:57], v[2:3]
	v_mov_b64_e32 v[58:59], v[2:3]
	v_mov_b64_e32 v[60:61], v[2:3]
	v_mov_b64_e32 v[62:63], v[2:3]
	v_mov_b64_e32 v[64:65], v[2:3]
	v_mov_b64_e32 v[66:67], v[2:3]
	v_mov_b64_e32 v[68:69], v[2:3]
	v_mov_b64_e32 v[70:71], v[2:3]
	v_mov_b64_e32 v[72:73], v[2:3]
	v_mov_b64_e32 v[74:75], v[2:3]
	v_mov_b64_e32 v[76:77], v[2:3]
	v_mov_b64_e32 v[78:79], v[2:3]
	v_mov_b64_e32 v[80:81], v[2:3]
	v_mov_b64_e32 v[82:83], v[2:3]
	v_mov_b64_e32 v[84:85], v[2:3]
	v_mov_b64_e32 v[86:87], v[2:3]
	v_mov_b64_e32 v[88:89], v[2:3]
	v_mov_b64_e32 v[90:91], v[2:3]
	v_mov_b64_e32 v[92:93], v[2:3]
	v_mov_b64_e32 v[94:95], v[2:3]
	v_mov_b64_e32 v[96:97], v[2:3]
	v_mov_b64_e32 v[98:99], v[2:3]
	v_mov_b64_e32 v[100:101], v[2:3]
	v_mov_b64_e32 v[102:103], v[2:3]
	v_mov_b64_e32 v[104:105], v[2:3]
	v_mov_b64_e32 v[106:107], v[2:3]
	v_mov_b64_e32 v[108:109], v[2:3]
	v_mov_b64_e32 v[110:111], v[2:3]
	v_mov_b64_e32 v[112:113], v[2:3]
	v_mov_b64_e32 v[114:115], v[2:3]
	v_mov_b64_e32 v[116:117], v[2:3]
	v_mov_b64_e32 v[118:119], v[2:3]
	v_mov_b64_e32 v[120:121], v[2:3]
	v_mov_b64_e32 v[122:123], v[2:3]
	v_mov_b64_e32 v[124:125], v[2:3]
	v_mov_b64_e32 v[126:127], v[2:3]
	v_mov_b64_e32 v[128:129], v[2:3]
	s_andn2_b64 vcc, exec, s[6:7]
	s_cbranch_vccnz .LBB0_724
	s_branch .LBB0_725

.LBB0_934:
	s_ashr_i32 s19, s18, 31
	s_lshl_b64 s[20:21], s[18:19], 19
	v_readlane_b32 s17, v254, 8
	s_add_u32 s20, s17, s20
	v_readlane_b32 s17, v254, 9
	s_addc_u32 s21, s17, s21
	s_and_b64 s[22:23], s[8:9], exec
	s_cselect_b32 s19, s21, s29
	s_cselect_b32 vcc_lo, s20, s28
	s_ashr_i32 s17, s16, 31
	s_lshl_b64 s[22:23], s[16:17], 19
	s_add_u32 s22, s35, s22
	s_addc_u32 s23, s36, s23
	s_and_b64 s[30:31], s[8:9], exec
	s_cselect_b32 s17, s23, s5
	s_cselect_b32 vcc_hi, s22, s4
	s_add_u32 s72, s4, 0x100
	s_addc_u32 s73, s5, 0
	s_add_u32 s28, s28, 0x40080
	v_mov_b32_e32 v2, 0
	s_addc_u32 s29, s29, 0
	s_mov_b32 s74, -2
	v_mov_b32_e32 v3, v2
	v_mov_b64_e32 v[4:5], v[2:3]
	v_mov_b64_e32 v[6:7], v[2:3]
	v_mov_b64_e32 v[8:9], v[2:3]
	v_mov_b64_e32 v[10:11], v[2:3]
	v_mov_b64_e32 v[12:13], v[2:3]
	v_mov_b64_e32 v[14:15], v[2:3]
	v_mov_b64_e32 v[16:17], v[2:3]
	v_mov_b64_e32 v[18:19], v[2:3]
	v_mov_b64_e32 v[20:21], v[2:3]
	v_mov_b64_e32 v[22:23], v[2:3]
	v_mov_b64_e32 v[24:25], v[2:3]
	v_mov_b64_e32 v[26:27], v[2:3]
	v_mov_b64_e32 v[28:29], v[2:3]
	v_mov_b64_e32 v[30:31], v[2:3]
	v_mov_b64_e32 v[32:33], v[2:3]
	v_mov_b64_e32 v[34:35], v[2:3]
	v_mov_b64_e32 v[36:37], v[2:3]
	v_mov_b64_e32 v[38:39], v[2:3]
	v_mov_b64_e32 v[40:41], v[2:3]
	v_mov_b64_e32 v[42:43], v[2:3]
	v_mov_b64_e32 v[44:45], v[2:3]
	v_mov_b64_e32 v[46:47], v[2:3]
	v_mov_b64_e32 v[48:49], v[2:3]
	v_mov_b64_e32 v[50:51], v[2:3]
	v_mov_b64_e32 v[52:53], v[2:3]
	v_mov_b64_e32 v[54:55], v[2:3]
	v_mov_b64_e32 v[56:57], v[2:3]
	v_mov_b64_e32 v[58:59], v[2:3]
	v_mov_b64_e32 v[60:61], v[2:3]
	v_mov_b64_e32 v[62:63], v[2:3]
	v_mov_b64_e32 v[64:65], v[2:3]
	v_mov_b64_e32 v[66:67], v[2:3]
	v_mov_b64_e32 v[68:69], v[2:3]
	v_mov_b64_e32 v[70:71], v[2:3]
	v_mov_b64_e32 v[72:73], v[2:3]
	v_mov_b64_e32 v[74:75], v[2:3]
	v_mov_b64_e32 v[76:77], v[2:3]
	v_mov_b64_e32 v[78:79], v[2:3]
	v_mov_b64_e32 v[80:81], v[2:3]
	v_mov_b64_e32 v[82:83], v[2:3]
	v_mov_b64_e32 v[84:85], v[2:3]
	v_mov_b64_e32 v[86:87], v[2:3]
	v_mov_b64_e32 v[88:89], v[2:3]
	v_mov_b64_e32 v[90:91], v[2:3]
	v_mov_b64_e32 v[92:93], v[2:3]
	v_mov_b64_e32 v[94:95], v[2:3]
	v_mov_b64_e32 v[96:97], v[2:3]
	v_mov_b64_e32 v[98:99], v[2:3]
	v_mov_b64_e32 v[100:101], v[2:3]
	v_mov_b64_e32 v[102:103], v[2:3]
	v_mov_b64_e32 v[104:105], v[2:3]
	v_mov_b64_e32 v[106:107], v[2:3]
	v_mov_b64_e32 v[108:109], v[2:3]
	v_mov_b64_e32 v[110:111], v[2:3]
	v_mov_b64_e32 v[112:113], v[2:3]
	v_mov_b64_e32 v[114:115], v[2:3]
	v_mov_b64_e32 v[116:117], v[2:3]
	v_mov_b64_e32 v[118:119], v[2:3]
	v_mov_b64_e32 v[120:121], v[2:3]
	v_mov_b64_e32 v[122:123], v[2:3]
	v_mov_b64_e32 v[124:125], v[2:3]
	v_mov_b64_e32 v[126:127], v[2:3]
	v_mov_b64_e32 v[128:129], v[2:3]

.LBB0_992:
	v_lshl_add_u64 v[10:11], s[4:5], 0, v[0:1]
	v_mov_b32_e32 v133, v1
	v_readlane_b32 s18, v254, 0
	v_and_b32_e32 v220, 15, v216
	v_and_b32_e32 v18, 48, v216
	v_lshlrev_b32_e32 v19, 2, v216
	v_lshl_add_u64 v[12:13], s[4:5], 0, v[132:133]
	v_mov_b32_e32 v137, v1
	v_readlane_b32 s19, v254, 1
	s_and_b32 s17, s31, 3
	s_lshl_b32 s6, s30, 13
	v_lshl_or_b32 v18, v220, 6, v18
	v_and_b32_e32 v19, 32, v19
	s_add_i32 m0, s26, 0x18000
	v_lshl_add_u64 v[10:11], v[10:11], 0, s[50:51]
	v_lshl_add_u64 v[14:15], s[18:19], 0, v[136:137]
	v_mov_b32_e32 v135, v1
	s_lshl_b32 s34, s30, 6
	v_bitop3_b32 v20, v18, s6, v19 bitop3:0xde
	s_lshl_b32 s6, s17, 12
	s_waitcnt vmcnt(2)
	s_barrier
	global_load_lds_dwordx4 v[10:11], off
	v_lshl_add_u64 v[10:11], v[12:13], 0, s[50:51]
	s_add_i32 m0, s26, 0x1a000
	s_add_i32 s35, s26, 0x8000
	s_add_i32 s36, s26, 0xa000
	v_lshl_add_u64 v[16:17], s[18:19], 0, v[134:135]
	v_bitop3_b32 v131, v18, s6, v19 bitop3:0xde
	global_load_lds_dwordx4 v[10:11], off
	v_lshl_add_u64 v[10:11], v[14:15], 0, s[50:51]
	s_mov_b32 m0, s35
	s_add_u32 s6, s4, 0xb0080
	global_load_lds_dwordx4 v[10:11], off
	v_lshl_add_u64 v[10:11], v[16:17], 0, s[50:51]
	s_mov_b32 m0, s36
	s_addc_u32 s7, s5, 0
	global_load_lds_dwordx4 v[10:11], off
	s_add_i32 m0, s26, 0x1c000
	v_lshl_add_u64 v[10:11], s[6:7], 0, v[0:1]
	global_load_lds_dwordx4 v[10:11], off
	v_lshl_add_u64 v[10:11], s[6:7], 0, v[132:133]
	s_add_i32 m0, s26, 0x1e000
	s_movk_i32 s9, 0xb00
	global_load_lds_dwordx4 v[10:11], off
	v_lshrrev_b32_e32 v10, 1, v2
	v_mul_lo_u32 v2, v3, s9
	s_mov_b32 s8, 0xb000
	v_mad_u64_u32 v[2:3], s[6:7], v10, s8, v[2:3]
	v_or_b32_e32 v2, v2, v4
	v_add_lshl_u32 v138, v2, v5, 1
	v_lshrrev_b32_e32 v3, 1, v7
	v_mul_lo_u32 v2, v6, s9
	v_mad_u64_u32 v[2:3], s[6:7], v3, s8, v[2:3]
	s_waitcnt vmcnt(6)
	v_or_b32_e32 v2, v2, v8
	v_readlane_b32 s6, v254, 40
	v_add_lshl_u32 v140, v2, v9, 1
	v_mov_b32_e32 v2, 0
	s_mov_b32 s14, s6
	v_readlane_b32 s6, v253, 62
	v_or_b32_e32 v130, s34, v220
	v_mov_b32_e32 v139, v1
	v_mov_b32_e32 v141, v1
	s_mov_b32 s37, 0
	v_add_u32_e32 v146, 0, v20
	s_mov_b32 s16, s6
	v_mov_b32_e32 v3, v2
	v_mov_b64_e32 v[4:5], v[2:3]
	v_mov_b64_e32 v[6:7], v[2:3]
	v_mov_b64_e32 v[8:9], v[2:3]
	v_mov_b64_e32 v[10:11], v[2:3]
	v_mov_b64_e32 v[12:13], v[2:3]
	v_mov_b64_e32 v[14:15], v[2:3]
	v_mov_b64_e32 v[16:17], v[2:3]
	v_mov_b64_e32 v[18:19], v[2:3]
	v_mov_b64_e32 v[20:21], v[2:3]
	v_mov_b64_e32 v[22:23], v[2:3]
	v_mov_b64_e32 v[24:25], v[2:3]
	v_mov_b64_e32 v[26:27], v[2:3]
	v_mov_b64_e32 v[28:29], v[2:3]
	v_mov_b64_e32 v[30:31], v[2:3]
	v_mov_b64_e32 v[32:33], v[2:3]
	v_mov_b64_e32 v[34:35], v[2:3]
	v_mov_b64_e32 v[36:37], v[2:3]
	v_mov_b64_e32 v[38:39], v[2:3]
	v_mov_b64_e32 v[40:41], v[2:3]
	v_mov_b64_e32 v[42:43], v[2:3]
	v_mov_b64_e32 v[44:45], v[2:3]
	v_mov_b64_e32 v[46:47], v[2:3]
	v_mov_b64_e32 v[48:49], v[2:3]
	v_mov_b64_e32 v[50:51], v[2:3]
	v_mov_b64_e32 v[52:53], v[2:3]
	v_mov_b64_e32 v[54:55], v[2:3]
	v_mov_b64_e32 v[56:57], v[2:3]
	v_mov_b64_e32 v[58:59], v[2:3]
	v_mov_b64_e32 v[60:61], v[2:3]
	v_mov_b64_e32 v[62:63], v[2:3]
	v_mov_b64_e32 v[64:65], v[2:3]
	v_mov_b64_e32 v[66:67], v[2:3]
	v_mov_b64_e32 v[68:69], v[2:3]
	v_mov_b64_e32 v[70:71], v[2:3]
	v_mov_b64_e32 v[72:73], v[2:3]
	v_mov_b64_e32 v[74:75], v[2:3]
	v_mov_b64_e32 v[76:77], v[2:3]
	v_mov_b64_e32 v[78:79], v[2:3]
	v_mov_b64_e32 v[80:81], v[2:3]
	v_mov_b64_e32 v[82:83], v[2:3]
	v_mov_b64_e32 v[84:85], v[2:3]
	v_mov_b64_e32 v[86:87], v[2:3]
	v_mov_b64_e32 v[88:89], v[2:3]
	v_mov_b64_e32 v[90:91], v[2:3]
	v_mov_b64_e32 v[92:93], v[2:3]
	v_mov_b64_e32 v[94:95], v[2:3]
	v_mov_b64_e32 v[96:97], v[2:3]
	v_mov_b64_e32 v[98:99], v[2:3]
	v_mov_b64_e32 v[100:101], v[2:3]
	v_mov_b64_e32 v[102:103], v[2:3]
	v_mov_b64_e32 v[104:105], v[2:3]
	v_mov_b64_e32 v[106:107], v[2:3]
	v_mov_b64_e32 v[108:109], v[2:3]
	v_mov_b64_e32 v[110:111], v[2:3]
	v_mov_b64_e32 v[112:113], v[2:3]
	v_mov_b64_e32 v[114:115], v[2:3]
	v_mov_b64_e32 v[116:117], v[2:3]
	v_mov_b64_e32 v[118:119], v[2:3]
	v_mov_b64_e32 v[120:121], v[2:3]
	v_mov_b64_e32 v[122:123], v[2:3]
	v_mov_b64_e32 v[124:125], v[2:3]
	v_mov_b64_e32 v[126:127], v[2:3]
	v_mov_b64_e32 v[128:129], v[2:3]
	s_barrier
	v_readlane_b32 s7, v253, 63

.LBB0_1004:
	s_add_u32 s4, s18, s22
	s_addc_u32 s5, s19, s23
	s_add_u32 s4, s4, 0x100
	s_addc_u32 s5, s5, 0
	s_add_u32 s75, s72, s22
	s_addc_u32 s76, s73, s23
	s_add_i32 s77, 0, 0x10000
	s_cmpk_eq_i32 s22, 0x1500
	s_cselect_b32 s25, s21, s5
	s_cselect_b32 s24, s20, s4
	v_add_u32_e32 v147, s77, v131
	s_cselect_b32 s5, s11, s76
	s_cselect_b32 s4, s10, s75
	s_add_i32 s75, 0, 0x14000
	ds_read_b128 v[148:151], v147
	ds_read_b128 v[152:155], v147 offset:1024
	ds_read_b128 v[156:159], v147 offset:2048
	ds_read_b128 v[160:163], v147 offset:3072
	v_add_u32_e32 v147, s75, v131
	ds_read_b128 v[164:167], v147
	ds_read_b128 v[168:171], v147 offset:1024
	ds_read_b128 v[172:175], v147 offset:2048
	ds_read_b128 v[176:179], v147 offset:3072
	v_lshl_add_u64 v[208:209], v[144:145], 0, s[22:23]
	s_add_i32 m0, s26, 0xc000
	ds_read_b128 v[180:183], v146
	ds_read_b128 v[184:187], v146 offset:1024
	ds_read_b128 v[188:191], v146 offset:2048
	ds_read_b128 v[192:195], v146 offset:3072
	ds_read_b128 v[196:199], v146 offset:4096
	ds_read_b128 v[200:203], v146 offset:5120
	ds_read_b128 v[204:207], v146 offset:6144
	ds_read_b128 v[230:233], v146 offset:7168
	global_load_lds_dwordx4 v[208:209], off
	v_lshl_add_u64 v[208:209], v[142:143], 0, s[22:23]
	s_add_i32 m0, s26, 0xe000
	s_nop 0
	global_load_lds_dwordx4 v[208:209], off
	s_waitcnt vmcnt(8)
	s_waitcnt lgkmcnt(0)
	s_barrier
	s_setprio 1
	s_waitcnt lgkmcnt(0)
	v_mfma_f32_16x16x32_bf16 v[126:129], v[148:151], v[180:183], v[126:129]
	v_mfma_f32_16x16x32_bf16 v[122:125], v[156:159], v[180:183], v[122:125]
	v_mfma_f32_16x16x32_bf16 v[114:117], v[148:151], v[188:191], v[114:117]
	v_mfma_f32_16x16x32_bf16 v[106:109], v[156:159], v[188:191], v[106:109]
	v_mfma_f32_16x16x32_bf16 v[98:101], v[148:151], v[196:199], v[98:101]
	v_mfma_f32_16x16x32_bf16 v[90:93], v[156:159], v[196:199], v[90:93]
	v_mfma_f32_16x16x32_bf16 v[82:85], v[148:151], v[204:207], v[82:85]
	v_mfma_f32_16x16x32_bf16 v[74:77], v[156:159], v[204:207], v[74:77]
	v_mfma_f32_16x16x32_bf16 v[126:129], v[152:155], v[184:187], v[126:129]
	v_mfma_f32_16x16x32_bf16 v[122:125], v[160:163], v[184:187], v[122:125]
	v_mfma_f32_16x16x32_bf16 v[114:117], v[152:155], v[192:195], v[114:117]
	v_mfma_f32_16x16x32_bf16 v[106:109], v[160:163], v[192:195], v[106:109]
	v_mfma_f32_16x16x32_bf16 v[98:101], v[152:155], v[200:203], v[98:101]
	v_mfma_f32_16x16x32_bf16 v[90:93], v[160:163], v[200:203], v[90:93]
	v_mfma_f32_16x16x32_bf16 v[82:85], v[152:155], v[230:233], v[82:85]
	v_mfma_f32_16x16x32_bf16 v[74:77], v[160:163], v[230:233], v[74:77]
	s_setprio 0
	s_setprio 1
	v_mfma_f32_16x16x32_bf16 v[118:121], v[164:167], v[180:183], v[118:121]
	v_mfma_f32_16x16x32_bf16 v[110:113], v[172:175], v[180:183], v[110:113]
	v_mfma_f32_16x16x32_bf16 v[102:105], v[164:167], v[188:191], v[102:105]
	v_mfma_f32_16x16x32_bf16 v[94:97], v[172:175], v[188:191], v[94:97]
	v_mfma_f32_16x16x32_bf16 v[86:89], v[164:167], v[196:199], v[86:89]
	v_mfma_f32_16x16x32_bf16 v[78:81], v[172:175], v[196:199], v[78:81]
	v_mfma_f32_16x16x32_bf16 v[70:73], v[164:167], v[204:207], v[70:73]
	v_mfma_f32_16x16x32_bf16 v[66:69], v[172:175], v[204:207], v[66:69]
	v_mfma_f32_16x16x32_bf16 v[118:121], v[168:171], v[184:187], v[118:121]
	v_mfma_f32_16x16x32_bf16 v[110:113], v[176:179], v[184:187], v[110:113]
	v_mfma_f32_16x16x32_bf16 v[102:105], v[168:171], v[192:195], v[102:105]
	v_mfma_f32_16x16x32_bf16 v[94:97], v[176:179], v[192:195], v[94:97]
	v_mfma_f32_16x16x32_bf16 v[86:89], v[168:171], v[200:203], v[86:89]
	v_mfma_f32_16x16x32_bf16 v[78:81], v[176:179], v[200:203], v[78:81]
	v_mfma_f32_16x16x32_bf16 v[70:73], v[168:171], v[230:233], v[70:73]
	v_mfma_f32_16x16x32_bf16 v[66:69], v[176:179], v[230:233], v[66:69]
	s_setprio 0
	s_barrier
	s_add_i32 s76, s77, s15
	v_lshl_add_u64 v[208:209], s[4:5], 0, v[0:1]
	s_mov_b32 m0, s76
	ds_read_b128 v[180:183], v146 offset:16384
	ds_read_b128 v[184:187], v146 offset:17408
	ds_read_b128 v[188:191], v146 offset:18432
	ds_read_b128 v[192:195], v146 offset:19456
	ds_read_b128 v[196:199], v146 offset:20480
	ds_read_b128 v[200:203], v146 offset:21504
	ds_read_b128 v[204:207], v146 offset:22528
	ds_read_b128 v[230:233], v146 offset:23552
	global_load_lds_dwordx4 v[208:209], off
	s_add_i32 m0, s76, 0x2000
	s_add_u32 s76, s4, 0xb0000
	v_lshl_add_u64 v[214:215], s[4:5], 0, v[132:133]
	s_addc_u32 s77, s5, 0
	s_add_i32 s75, s75, s15
	global_load_lds_dwordx4 v[214:215], off
	v_lshl_add_u64 v[218:219], s[76:77], 0, v[0:1]
	s_mov_b32 m0, s75
	v_lshl_add_u64 v[226:227], s[24:25], 0, v[134:135]
	global_load_lds_dwordx4 v[218:219], off
	v_lshl_add_u64 v[218:219], s[76:77], 0, v[132:133]
	s_add_i32 m0, s75, 0x2000
	s_nop 0
	global_load_lds_dwordx4 v[218:219], off
	v_lshl_add_u64 v[218:219], s[24:25], 0, v[136:137]
	s_mov_b32 m0, s26
	s_nop 0
	global_load_lds_dwordx4 v[218:219], off
	s_mov_b32 m0, s27
	s_nop 0
	global_load_lds_dwordx4 v[226:227], off
	s_waitcnt vmcnt(8)
	s_waitcnt lgkmcnt(0)
	s_barrier
	s_setprio 1
	s_waitcnt lgkmcnt(0)
	v_mfma_f32_16x16x32_bf16 v[62:65], v[148:151], v[180:183], v[62:65]
	v_mfma_f32_16x16x32_bf16 v[58:61], v[156:159], v[180:183], v[58:61]
	v_mfma_f32_16x16x32_bf16 v[50:53], v[148:151], v[188:191], v[50:53]
	v_mfma_f32_16x16x32_bf16 v[42:45], v[156:159], v[188:191], v[42:45]
	v_mfma_f32_16x16x32_bf16 v[34:37], v[148:151], v[196:199], v[34:37]
	v_mfma_f32_16x16x32_bf16 v[26:29], v[156:159], v[196:199], v[26:29]
	v_mfma_f32_16x16x32_bf16 v[18:21], v[148:151], v[204:207], v[18:21]
	v_mfma_f32_16x16x32_bf16 v[10:13], v[156:159], v[204:207], v[10:13]
	v_mfma_f32_16x16x32_bf16 v[62:65], v[152:155], v[184:187], v[62:65]
	v_mfma_f32_16x16x32_bf16 v[58:61], v[160:163], v[184:187], v[58:61]
	v_mfma_f32_16x16x32_bf16 v[50:53], v[152:155], v[192:195], v[50:53]
	v_mfma_f32_16x16x32_bf16 v[42:45], v[160:163], v[192:195], v[42:45]
	v_mfma_f32_16x16x32_bf16 v[34:37], v[152:155], v[200:203], v[34:37]
	v_mfma_f32_16x16x32_bf16 v[26:29], v[160:163], v[200:203], v[26:29]
	v_mfma_f32_16x16x32_bf16 v[18:21], v[152:155], v[230:233], v[18:21]
	v_mfma_f32_16x16x32_bf16 v[10:13], v[160:163], v[230:233], v[10:13]
	s_setprio 0
	s_setprio 1
	v_mfma_f32_16x16x32_bf16 v[54:57], v[164:167], v[180:183], v[54:57]
	v_mfma_f32_16x16x32_bf16 v[46:49], v[172:175], v[180:183], v[46:49]
	v_mfma_f32_16x16x32_bf16 v[38:41], v[164:167], v[188:191], v[38:41]
	v_mfma_f32_16x16x32_bf16 v[30:33], v[172:175], v[188:191], v[30:33]
	v_mfma_f32_16x16x32_bf16 v[22:25], v[164:167], v[196:199], v[22:25]
	v_mfma_f32_16x16x32_bf16 v[14:17], v[172:175], v[196:199], v[14:17]
	v_mfma_f32_16x16x32_bf16 v[6:9], v[164:167], v[204:207], v[6:9]
	v_mfma_f32_16x16x32_bf16 v[2:5], v[172:175], v[204:207], v[2:5]
	v_mfma_f32_16x16x32_bf16 v[54:57], v[168:171], v[184:187], v[54:57]
	v_mfma_f32_16x16x32_bf16 v[46:49], v[176:179], v[184:187], v[46:49]
	v_mfma_f32_16x16x32_bf16 v[38:41], v[168:171], v[192:195], v[38:41]
	v_mfma_f32_16x16x32_bf16 v[30:33], v[176:179], v[192:195], v[30:33]
	v_mfma_f32_16x16x32_bf16 v[22:25], v[168:171], v[200:203], v[22:25]
	v_mfma_f32_16x16x32_bf16 v[14:17], v[176:179], v[200:203], v[14:17]
	v_mfma_f32_16x16x32_bf16 v[6:9], v[168:171], v[230:233], v[6:9]
	v_mfma_f32_16x16x32_bf16 v[2:5], v[176:179], v[230:233], v[2:5]
	s_setprio 0
	s_barrier
	s_add_i32 s75, 0, 0x18000
	v_add_u32_e32 v147, s75, v131
	s_add_i32 s76, 0, 0x1c000
	ds_read_b128 v[148:151], v147
	ds_read_b128 v[152:155], v147 offset:1024
	ds_read_b128 v[156:159], v147 offset:2048
	ds_read_b128 v[160:163], v147 offset:3072
	v_add_u32_e32 v147, s76, v131
	ds_read_b128 v[164:167], v147
	ds_read_b128 v[168:171], v147 offset:1024
	ds_read_b128 v[172:175], v147 offset:2048
	ds_read_b128 v[176:179], v147 offset:3072
	s_add_u32 s24, s24, 0xb0000
	s_addc_u32 s25, s25, 0
	s_mov_b32 m0, s28
	v_lshl_add_u64 v[228:229], s[24:25], 0, v[136:137]
	ds_read_b128 v[180:183], v146 offset:32768
	ds_read_b128 v[184:187], v146 offset:33792
	ds_read_b128 v[188:191], v146 offset:34816
	ds_read_b128 v[192:195], v146 offset:35840
	ds_read_b128 v[196:199], v146 offset:36864
	ds_read_b128 v[200:203], v146 offset:37888
	ds_read_b128 v[204:207], v146 offset:38912
	ds_read_b128 v[230:233], v146 offset:39936
	global_load_lds_dwordx4 v[228:229], off
	v_lshl_add_u64 v[228:229], s[24:25], 0, v[134:135]
	s_mov_b32 m0, s29
	s_nop 0
	global_load_lds_dwordx4 v[228:229], off
	s_waitcnt vmcnt(8)
	s_waitcnt lgkmcnt(0)
	s_barrier
	s_setprio 1
	s_waitcnt lgkmcnt(0)
	v_mfma_f32_16x16x32_bf16 v[126:129], v[148:151], v[180:183], v[126:129]
	v_mfma_f32_16x16x32_bf16 v[122:125], v[156:159], v[180:183], v[122:125]
	v_mfma_f32_16x16x32_bf16 v[114:117], v[148:151], v[188:191], v[114:117]
	v_mfma_f32_16x16x32_bf16 v[106:109], v[156:159], v[188:191], v[106:109]
	v_mfma_f32_16x16x32_bf16 v[98:101], v[148:151], v[196:199], v[98:101]
	v_mfma_f32_16x16x32_bf16 v[90:93], v[156:159], v[196:199], v[90:93]
	v_mfma_f32_16x16x32_bf16 v[82:85], v[148:151], v[204:207], v[82:85]
	v_mfma_f32_16x16x32_bf16 v[74:77], v[156:159], v[204:207], v[74:77]
	v_mfma_f32_16x16x32_bf16 v[126:129], v[152:155], v[184:187], v[126:129]
	v_mfma_f32_16x16x32_bf16 v[122:125], v[160:163], v[184:187], v[122:125]
	v_mfma_f32_16x16x32_bf16 v[114:117], v[152:155], v[192:195], v[114:117]
	v_mfma_f32_16x16x32_bf16 v[106:109], v[160:163], v[192:195], v[106:109]
	v_mfma_f32_16x16x32_bf16 v[98:101], v[152:155], v[200:203], v[98:101]
	v_mfma_f32_16x16x32_bf16 v[90:93], v[160:163], v[200:203], v[90:93]
	v_mfma_f32_16x16x32_bf16 v[82:85], v[152:155], v[230:233], v[82:85]
	v_mfma_f32_16x16x32_bf16 v[74:77], v[160:163], v[230:233], v[74:77]
	s_setprio 0
	s_setprio 1
	v_mfma_f32_16x16x32_bf16 v[118:121], v[164:167], v[180:183], v[118:121]
	v_mfma_f32_16x16x32_bf16 v[110:113], v[172:175], v[180:183], v[110:113]
	v_mfma_f32_16x16x32_bf16 v[102:105], v[164:167], v[188:191], v[102:105]
	v_mfma_f32_16x16x32_bf16 v[94:97], v[172:175], v[188:191], v[94:97]
	v_mfma_f32_16x16x32_bf16 v[86:89], v[164:167], v[196:199], v[86:89]
	v_mfma_f32_16x16x32_bf16 v[78:81], v[172:175], v[196:199], v[78:81]
	v_mfma_f32_16x16x32_bf16 v[70:73], v[164:167], v[204:207], v[70:73]
	v_mfma_f32_16x16x32_bf16 v[66:69], v[172:175], v[204:207], v[66:69]
	v_mfma_f32_16x16x32_bf16 v[118:121], v[168:171], v[184:187], v[118:121]
	v_mfma_f32_16x16x32_bf16 v[110:113], v[176:179], v[184:187], v[110:113]
	v_mfma_f32_16x16x32_bf16 v[102:105], v[168:171], v[192:195], v[102:105]
	v_mfma_f32_16x16x32_bf16 v[94:97], v[176:179], v[192:195], v[94:97]
	v_mfma_f32_16x16x32_bf16 v[86:89], v[168:171], v[200:203], v[86:89]
	v_mfma_f32_16x16x32_bf16 v[78:81], v[176:179], v[200:203], v[78:81]
	v_mfma_f32_16x16x32_bf16 v[70:73], v[168:171], v[230:233], v[70:73]
	v_mfma_f32_16x16x32_bf16 v[66:69], v[176:179], v[230:233], v[66:69]
	s_setprio 0
	s_barrier
	s_add_i32 s24, s75, s15
	v_lshl_add_u64 v[208:209], v[208:209], 0, s[50:51]
	s_mov_b32 m0, s24
	ds_read_b128 v[180:183], v146 offset:49152
	ds_read_b128 v[184:187], v146 offset:50176
	ds_read_b128 v[188:191], v146 offset:51200
	ds_read_b128 v[192:195], v146 offset:52224
	ds_read_b128 v[196:199], v146 offset:53248
	ds_read_b128 v[200:203], v146 offset:54272
	ds_read_b128 v[204:207], v146 offset:55296
	ds_read_b128 v[230:233], v146 offset:56320
	global_load_lds_dwordx4 v[208:209], off
	s_add_i32 m0, s24, 0x2000
	s_add_u32 s4, s4, 0xb0080
	v_lshl_add_u64 v[208:209], v[214:215], 0, s[50:51]
	s_addc_u32 s5, s5, 0
	s_add_i32 s24, s76, s15
	global_load_lds_dwordx4 v[208:209], off
	v_lshl_add_u64 v[208:209], s[4:5], 0, v[0:1]
	s_mov_b32 m0, s24
	s_nop 0
	global_load_lds_dwordx4 v[208:209], off
	v_lshl_add_u64 v[208:209], s[4:5], 0, v[132:133]
	s_add_i32 m0, s24, 0x2000
	s_nop 0
	global_load_lds_dwordx4 v[208:209], off
	v_lshl_add_u64 v[208:209], v[218:219], 0, s[50:51]
	s_mov_b32 m0, s35
	s_nop 0
	global_load_lds_dwordx4 v[208:209], off
	v_lshl_add_u64 v[208:209], v[226:227], 0, s[50:51]
	s_mov_b32 m0, s36
	s_nop 0
	global_load_lds_dwordx4 v[208:209], off
	s_waitcnt vmcnt(8)
	s_waitcnt lgkmcnt(0)
	s_barrier
	s_setprio 1
	s_waitcnt lgkmcnt(0)
	v_mfma_f32_16x16x32_bf16 v[62:65], v[148:151], v[180:183], v[62:65]
	v_mfma_f32_16x16x32_bf16 v[58:61], v[156:159], v[180:183], v[58:61]
	v_mfma_f32_16x16x32_bf16 v[50:53], v[148:151], v[188:191], v[50:53]
	v_mfma_f32_16x16x32_bf16 v[42:45], v[156:159], v[188:191], v[42:45]
	v_mfma_f32_16x16x32_bf16 v[34:37], v[148:151], v[196:199], v[34:37]
	v_mfma_f32_16x16x32_bf16 v[26:29], v[156:159], v[196:199], v[26:29]
	v_mfma_f32_16x16x32_bf16 v[18:21], v[148:151], v[204:207], v[18:21]
	v_mfma_f32_16x16x32_bf16 v[10:13], v[156:159], v[204:207], v[10:13]
	v_mfma_f32_16x16x32_bf16 v[62:65], v[152:155], v[184:187], v[62:65]
	v_mfma_f32_16x16x32_bf16 v[58:61], v[160:163], v[184:187], v[58:61]
	v_mfma_f32_16x16x32_bf16 v[50:53], v[152:155], v[192:195], v[50:53]
	v_mfma_f32_16x16x32_bf16 v[42:45], v[160:163], v[192:195], v[42:45]
	v_mfma_f32_16x16x32_bf16 v[34:37], v[152:155], v[200:203], v[34:37]
	v_mfma_f32_16x16x32_bf16 v[26:29], v[160:163], v[200:203], v[26:29]
	v_mfma_f32_16x16x32_bf16 v[18:21], v[152:155], v[230:233], v[18:21]
	v_mfma_f32_16x16x32_bf16 v[10:13], v[160:163], v[230:233], v[10:13]
	s_setprio 0
	s_setprio 1
	v_mfma_f32_16x16x32_bf16 v[54:57], v[164:167], v[180:183], v[54:57]
	v_mfma_f32_16x16x32_bf16 v[46:49], v[172:175], v[180:183], v[46:49]
	v_mfma_f32_16x16x32_bf16 v[38:41], v[164:167], v[188:191], v[38:41]
	v_mfma_f32_16x16x32_bf16 v[30:33], v[172:175], v[188:191], v[30:33]
	v_mfma_f32_16x16x32_bf16 v[22:25], v[164:167], v[196:199], v[22:25]
	v_mfma_f32_16x16x32_bf16 v[14:17], v[172:175], v[196:199], v[14:17]
	v_mfma_f32_16x16x32_bf16 v[6:9], v[164:167], v[204:207], v[6:9]
	v_mfma_f32_16x16x32_bf16 v[2:5], v[172:175], v[204:207], v[2:5]
	v_mfma_f32_16x16x32_bf16 v[54:57], v[168:171], v[184:187], v[54:57]
	v_mfma_f32_16x16x32_bf16 v[46:49], v[176:179], v[184:187], v[46:49]
	v_mfma_f32_16x16x32_bf16 v[38:41], v[168:171], v[192:195], v[38:41]
	v_mfma_f32_16x16x32_bf16 v[30:33], v[176:179], v[192:195], v[30:33]
	v_mfma_f32_16x16x32_bf16 v[22:25], v[168:171], v[200:203], v[22:25]
	v_mfma_f32_16x16x32_bf16 v[14:17], v[176:179], v[200:203], v[14:17]
	v_mfma_f32_16x16x32_bf16 v[6:9], v[168:171], v[230:233], v[6:9]
	v_mfma_f32_16x16x32_bf16 v[2:5], v[176:179], v[230:233], v[2:5]
	s_setprio 0
	s_barrier
	s_add_i32 s74, s74, 2
	s_add_u32 s22, s22, 0x100
	s_addc_u32 s23, s23, 0
	s_cmp_gt_u32 s74, 41
	s_cbranch_scc0 .LBB0_1004
	s_add_u32 s4, s72, 0xffffff00
	s_addc_u32 s5, s73, -1
	s_and_b64 vcc, exec, s[8:9]
	s_cbranch_vccnz .LBB0_1007
	v_mov_b32_e32 v2, 0
	s_mov_b32 s14, s38
	s_mov_b32 s16, s39
	s_mov_b64 s[18:19], s[20:21]
	s_mov_b32 s37, s71
	v_mov_b32_e32 v3, v2
	v_mov_b64_e32 v[4:5], v[2:3]
	v_mov_b64_e32 v[6:7], v[2:3]
	v_mov_b64_e32 v[8:9], v[2:3]
	v_mov_b64_e32 v[10:11], v[2:3]
	v_mov_b64_e32 v[12:13], v[2:3]
	v_mov_b64_e32 v[14:15], v[2:3]
	v_mov_b64_e32 v[16:17], v[2:3]
	v_mov_b64_e32 v[18:19], v[2:3]
	v_mov_b64_e32 v[20:21], v[2:3]
	v_mov_b64_e32 v[22:23], v[2:3]
	v_mov_b64_e32 v[24:25], v[2:3]
	v_mov_b64_e32 v[26:27], v[2:3]
	v_mov_b64_e32 v[28:29], v[2:3]
	v_mov_b64_e32 v[30:31], v[2:3]
	v_mov_b64_e32 v[32:33], v[2:3]
	v_mov_b64_e32 v[34:35], v[2:3]
	v_mov_b64_e32 v[36:37], v[2:3]
	v_mov_b64_e32 v[38:39], v[2:3]
	v_mov_b64_e32 v[40:41], v[2:3]
	v_mov_b64_e32 v[42:43], v[2:3]
	v_mov_b64_e32 v[44:45], v[2:3]
	v_mov_b64_e32 v[46:47], v[2:3]
	v_mov_b64_e32 v[48:49], v[2:3]
	v_mov_b64_e32 v[50:51], v[2:3]
	v_mov_b64_e32 v[52:53], v[2:3]
	v_mov_b64_e32 v[54:55], v[2:3]
	v_mov_b64_e32 v[56:57], v[2:3]
	v_mov_b64_e32 v[58:59], v[2:3]
	v_mov_b64_e32 v[60:61], v[2:3]
	v_mov_b64_e32 v[62:63], v[2:3]
	v_mov_b64_e32 v[64:65], v[2:3]
	v_mov_b64_e32 v[66:67], v[2:3]
	v_mov_b64_e32 v[68:69], v[2:3]
	v_mov_b64_e32 v[70:71], v[2:3]
	v_mov_b64_e32 v[72:73], v[2:3]
	v_mov_b64_e32 v[74:75], v[2:3]
	v_mov_b64_e32 v[76:77], v[2:3]
	v_mov_b64_e32 v[78:79], v[2:3]
	v_mov_b64_e32 v[80:81], v[2:3]
	v_mov_b64_e32 v[82:83], v[2:3]
	v_mov_b64_e32 v[84:85], v[2:3]
	v_mov_b64_e32 v[86:87], v[2:3]
	v_mov_b64_e32 v[88:89], v[2:3]
	v_mov_b64_e32 v[90:91], v[2:3]
	v_mov_b64_e32 v[92:93], v[2:3]
	v_mov_b64_e32 v[94:95], v[2:3]
	v_mov_b64_e32 v[96:97], v[2:3]
	v_mov_b64_e32 v[98:99], v[2:3]
	v_mov_b64_e32 v[100:101], v[2:3]
	v_mov_b64_e32 v[102:103], v[2:3]
	v_mov_b64_e32 v[104:105], v[2:3]
	v_mov_b64_e32 v[106:107], v[2:3]
	v_mov_b64_e32 v[108:109], v[2:3]
	v_mov_b64_e32 v[110:111], v[2:3]
	v_mov_b64_e32 v[112:113], v[2:3]
	v_mov_b64_e32 v[114:115], v[2:3]
	v_mov_b64_e32 v[116:117], v[2:3]
	v_mov_b64_e32 v[118:119], v[2:3]
	v_mov_b64_e32 v[120:121], v[2:3]
	v_mov_b64_e32 v[122:123], v[2:3]
	v_mov_b64_e32 v[124:125], v[2:3]
	v_mov_b64_e32 v[126:127], v[2:3]
	v_mov_b64_e32 v[128:129], v[2:3]
	s_andn2_b64 vcc, exec, s[6:7]
	s_cbranch_vccnz .LBB0_1008
	s_branch .LBB0_1009

.LBB0_1214:
	v_lshl_add_u64 v[10:11], s[20:21], 0, v[0:1]
	v_mov_b32_e32 v133, v1
	v_readlane_b32 s16, v254, 0
	v_and_b32_e32 v217, 15, v216
	v_and_b32_e32 v18, 48, v216
	v_lshlrev_b32_e32 v19, 2, v216
	v_lshl_add_u64 v[12:13], s[20:21], 0, v[132:133]
	v_mov_b32_e32 v137, v1
	v_readlane_b32 s17, v254, 1
	s_and_b32 s27, s12, 3
	s_lshl_b32 s4, s11, 13
	v_lshl_or_b32 v18, v217, 6, v18
	v_and_b32_e32 v19, 32, v19
	s_add_i32 m0, s29, 0x18000
	v_lshl_add_u64 v[10:11], v[10:11], 0, s[50:51]
	v_lshl_add_u64 v[14:15], s[16:17], 0, v[136:137]
	v_mov_b32_e32 v135, v1
	s_lshl_b32 s26, s11, 6
	v_bitop3_b32 v20, v18, s4, v19 bitop3:0xde
	s_lshl_b32 s4, s27, 12
	s_waitcnt vmcnt(2)
	s_barrier
	global_load_lds_dwordx4 v[10:11], off
	v_lshl_add_u64 v[10:11], v[12:13], 0, s[50:51]
	s_add_i32 m0, s29, 0x1a000
	s_add_i32 s35, s29, 0x8000
	s_add_i32 s36, s29, 0xa000
	v_lshl_add_u64 v[16:17], s[16:17], 0, v[134:135]
	v_bitop3_b32 v131, v18, s4, v19 bitop3:0xde
	global_load_lds_dwordx4 v[10:11], off
	v_lshl_add_u64 v[10:11], v[14:15], 0, s[50:51]
	s_mov_b32 m0, s35
	s_add_u32 s4, s20, 0xb0080
	global_load_lds_dwordx4 v[10:11], off
	v_lshl_add_u64 v[10:11], v[16:17], 0, s[50:51]
	s_mov_b32 m0, s36
	s_addc_u32 s5, s21, 0
	global_load_lds_dwordx4 v[10:11], off
	s_add_i32 m0, s29, 0x1c000
	v_lshl_add_u64 v[10:11], s[4:5], 0, v[0:1]
	global_load_lds_dwordx4 v[10:11], off
	v_lshl_add_u64 v[10:11], s[4:5], 0, v[132:133]
	s_add_i32 m0, s29, 0x1e000
	s_movk_i32 s7, 0xb00
	global_load_lds_dwordx4 v[10:11], off
	v_lshrrev_b32_e32 v10, 1, v2
	v_mul_lo_u32 v2, v3, s7
	s_mov_b32 s6, 0xb000
	v_mad_u64_u32 v[2:3], s[4:5], v10, s6, v[2:3]
	v_or_b32_e32 v2, v2, v4
	v_add_lshl_u32 v138, v2, v5, 1
	v_lshrrev_b32_e32 v3, 1, v7
	v_mul_lo_u32 v2, v6, s7
	v_mad_u64_u32 v[2:3], s[4:5], v3, s6, v[2:3]
	s_waitcnt vmcnt(6)
	v_or_b32_e32 v2, v2, v8
	v_readlane_b32 s4, v254, 40
	v_add_lshl_u32 v140, v2, v9, 1
	v_mov_b32_e32 v2, 0
	s_mov_b32 s14, s4
	v_readlane_b32 s4, v253, 62
	v_or_b32_e32 v130, s26, v217
	v_mov_b32_e32 v139, v1
	v_mov_b32_e32 v141, v1
	s_mov_b32 s37, 0
	v_add_u32_e32 v146, 0, v20
	s_mov_b32 s10, s4
	v_mov_b32_e32 v3, v2
	v_mov_b64_e32 v[4:5], v[2:3]
	v_mov_b64_e32 v[6:7], v[2:3]
	v_mov_b64_e32 v[8:9], v[2:3]
	v_mov_b64_e32 v[10:11], v[2:3]
	v_mov_b64_e32 v[12:13], v[2:3]
	v_mov_b64_e32 v[14:15], v[2:3]
	v_mov_b64_e32 v[16:17], v[2:3]
	v_mov_b64_e32 v[18:19], v[2:3]
	v_mov_b64_e32 v[20:21], v[2:3]
	v_mov_b64_e32 v[22:23], v[2:3]
	v_mov_b64_e32 v[24:25], v[2:3]
	v_mov_b64_e32 v[26:27], v[2:3]
	v_mov_b64_e32 v[28:29], v[2:3]
	v_mov_b64_e32 v[30:31], v[2:3]
	v_mov_b64_e32 v[32:33], v[2:3]
	v_mov_b64_e32 v[34:35], v[2:3]
	v_mov_b64_e32 v[36:37], v[2:3]
	v_mov_b64_e32 v[38:39], v[2:3]
	v_mov_b64_e32 v[40:41], v[2:3]
	v_mov_b64_e32 v[42:43], v[2:3]
	v_mov_b64_e32 v[44:45], v[2:3]
	v_mov_b64_e32 v[46:47], v[2:3]
	v_mov_b64_e32 v[48:49], v[2:3]
	v_mov_b64_e32 v[50:51], v[2:3]
	v_mov_b64_e32 v[52:53], v[2:3]
	v_mov_b64_e32 v[54:55], v[2:3]
	v_mov_b64_e32 v[56:57], v[2:3]
	v_mov_b64_e32 v[58:59], v[2:3]
	v_mov_b64_e32 v[60:61], v[2:3]
	v_mov_b64_e32 v[62:63], v[2:3]
	v_mov_b64_e32 v[64:65], v[2:3]
	v_mov_b64_e32 v[66:67], v[2:3]
	v_mov_b64_e32 v[68:69], v[2:3]
	v_mov_b64_e32 v[70:71], v[2:3]
	v_mov_b64_e32 v[72:73], v[2:3]
	v_mov_b64_e32 v[74:75], v[2:3]
	v_mov_b64_e32 v[76:77], v[2:3]
	v_mov_b64_e32 v[78:79], v[2:3]
	v_mov_b64_e32 v[80:81], v[2:3]
	v_mov_b64_e32 v[82:83], v[2:3]
	v_mov_b64_e32 v[84:85], v[2:3]
	v_mov_b64_e32 v[86:87], v[2:3]
	v_mov_b64_e32 v[88:89], v[2:3]
	v_mov_b64_e32 v[90:91], v[2:3]
	v_mov_b64_e32 v[92:93], v[2:3]
	v_mov_b64_e32 v[94:95], v[2:3]
	v_mov_b64_e32 v[96:97], v[2:3]
	v_mov_b64_e32 v[98:99], v[2:3]
	v_mov_b64_e32 v[100:101], v[2:3]
	v_mov_b64_e32 v[102:103], v[2:3]
	v_mov_b64_e32 v[104:105], v[2:3]
	v_mov_b64_e32 v[106:107], v[2:3]
	v_mov_b64_e32 v[108:109], v[2:3]
	v_mov_b64_e32 v[110:111], v[2:3]
	v_mov_b64_e32 v[112:113], v[2:3]
	v_mov_b64_e32 v[114:115], v[2:3]
	v_mov_b64_e32 v[116:117], v[2:3]
	v_mov_b64_e32 v[118:119], v[2:3]
	v_mov_b64_e32 v[120:121], v[2:3]
	v_mov_b64_e32 v[122:123], v[2:3]
	v_mov_b64_e32 v[124:125], v[2:3]
	v_mov_b64_e32 v[126:127], v[2:3]
	v_mov_b64_e32 v[128:129], v[2:3]
	s_barrier
	v_readlane_b32 s5, v253, 63

.LBB0_1226:
	s_add_u32 s22, s16, s20
	s_addc_u32 s23, s17, s21
	s_add_u32 s22, s22, 0x100
	s_addc_u32 s23, s23, 0
	s_add_u32 s75, s72, s20
	s_addc_u32 s76, s73, s21
	s_add_i32 s77, 0, 0x10000
	s_cmpk_eq_i32 s20, 0x1500
	s_cselect_b32 s25, s19, s23
	s_cselect_b32 s24, s18, s22
	v_add_u32_e32 v147, s77, v131
	s_cselect_b32 s23, s9, s76
	s_cselect_b32 s22, s8, s75
	s_add_i32 s75, 0, 0x14000
	ds_read_b128 v[148:151], v147
	ds_read_b128 v[152:155], v147 offset:1024
	ds_read_b128 v[156:159], v147 offset:2048
	ds_read_b128 v[160:163], v147 offset:3072
	v_add_u32_e32 v147, s75, v131
	ds_read_b128 v[164:167], v147
	ds_read_b128 v[168:171], v147 offset:1024
	ds_read_b128 v[172:175], v147 offset:2048
	ds_read_b128 v[176:179], v147 offset:3072
	v_lshl_add_u64 v[208:209], v[144:145], 0, s[20:21]
	s_add_i32 m0, s29, 0xc000
	ds_read_b128 v[180:183], v146
	ds_read_b128 v[184:187], v146 offset:1024
	ds_read_b128 v[188:191], v146 offset:2048
	ds_read_b128 v[192:195], v146 offset:3072
	ds_read_b128 v[196:199], v146 offset:4096
	ds_read_b128 v[200:203], v146 offset:5120
	ds_read_b128 v[204:207], v146 offset:6144
	ds_read_b128 v[218:221], v146 offset:7168
	global_load_lds_dwordx4 v[208:209], off
	v_lshl_add_u64 v[208:209], v[142:143], 0, s[20:21]
	s_add_i32 m0, s29, 0xe000
	s_nop 0
	global_load_lds_dwordx4 v[208:209], off
	s_waitcnt vmcnt(8)
	s_waitcnt lgkmcnt(0)
	s_barrier
	s_setprio 1
	s_waitcnt lgkmcnt(0)
	v_mfma_f32_16x16x32_bf16 v[126:129], v[148:151], v[180:183], v[126:129]
	v_mfma_f32_16x16x32_bf16 v[122:125], v[156:159], v[180:183], v[122:125]
	v_mfma_f32_16x16x32_bf16 v[114:117], v[148:151], v[188:191], v[114:117]
	v_mfma_f32_16x16x32_bf16 v[106:109], v[156:159], v[188:191], v[106:109]
	v_mfma_f32_16x16x32_bf16 v[98:101], v[148:151], v[196:199], v[98:101]
	v_mfma_f32_16x16x32_bf16 v[90:93], v[156:159], v[196:199], v[90:93]
	v_mfma_f32_16x16x32_bf16 v[82:85], v[148:151], v[204:207], v[82:85]
	v_mfma_f32_16x16x32_bf16 v[74:77], v[156:159], v[204:207], v[74:77]
	v_mfma_f32_16x16x32_bf16 v[126:129], v[152:155], v[184:187], v[126:129]
	v_mfma_f32_16x16x32_bf16 v[122:125], v[160:163], v[184:187], v[122:125]
	v_mfma_f32_16x16x32_bf16 v[114:117], v[152:155], v[192:195], v[114:117]
	v_mfma_f32_16x16x32_bf16 v[106:109], v[160:163], v[192:195], v[106:109]
	v_mfma_f32_16x16x32_bf16 v[98:101], v[152:155], v[200:203], v[98:101]
	v_mfma_f32_16x16x32_bf16 v[90:93], v[160:163], v[200:203], v[90:93]
	v_mfma_f32_16x16x32_bf16 v[82:85], v[152:155], v[218:221], v[82:85]
	v_mfma_f32_16x16x32_bf16 v[74:77], v[160:163], v[218:221], v[74:77]
	s_setprio 0
	s_setprio 1
	v_mfma_f32_16x16x32_bf16 v[118:121], v[164:167], v[180:183], v[118:121]
	v_mfma_f32_16x16x32_bf16 v[110:113], v[172:175], v[180:183], v[110:113]
	v_mfma_f32_16x16x32_bf16 v[102:105], v[164:167], v[188:191], v[102:105]
	v_mfma_f32_16x16x32_bf16 v[94:97], v[172:175], v[188:191], v[94:97]
	v_mfma_f32_16x16x32_bf16 v[86:89], v[164:167], v[196:199], v[86:89]
	v_mfma_f32_16x16x32_bf16 v[78:81], v[172:175], v[196:199], v[78:81]
	v_mfma_f32_16x16x32_bf16 v[70:73], v[164:167], v[204:207], v[70:73]
	v_mfma_f32_16x16x32_bf16 v[66:69], v[172:175], v[204:207], v[66:69]
	v_mfma_f32_16x16x32_bf16 v[118:121], v[168:171], v[184:187], v[118:121]
	v_mfma_f32_16x16x32_bf16 v[110:113], v[176:179], v[184:187], v[110:113]
	v_mfma_f32_16x16x32_bf16 v[102:105], v[168:171], v[192:195], v[102:105]
	v_mfma_f32_16x16x32_bf16 v[94:97], v[176:179], v[192:195], v[94:97]
	v_mfma_f32_16x16x32_bf16 v[86:89], v[168:171], v[200:203], v[86:89]
	v_mfma_f32_16x16x32_bf16 v[78:81], v[176:179], v[200:203], v[78:81]
	v_mfma_f32_16x16x32_bf16 v[70:73], v[168:171], v[218:221], v[70:73]
	v_mfma_f32_16x16x32_bf16 v[66:69], v[176:179], v[218:221], v[66:69]
	s_setprio 0
	s_barrier
	s_add_i32 s76, s77, s28
	v_lshl_add_u64 v[208:209], s[22:23], 0, v[0:1]
	s_mov_b32 m0, s76
	ds_read_b128 v[180:183], v146 offset:16384
	ds_read_b128 v[184:187], v146 offset:17408
	ds_read_b128 v[188:191], v146 offset:18432
	ds_read_b128 v[192:195], v146 offset:19456
	ds_read_b128 v[196:199], v146 offset:20480
	ds_read_b128 v[200:203], v146 offset:21504
	ds_read_b128 v[204:207], v146 offset:22528
	ds_read_b128 v[218:221], v146 offset:23552
	global_load_lds_dwordx4 v[208:209], off
	s_add_i32 m0, s76, 0x2000
	s_add_u32 s76, s22, 0xb0000
	v_lshl_add_u64 v[214:215], s[22:23], 0, v[132:133]
	s_addc_u32 s77, s23, 0
	s_add_i32 s75, s75, s28
	global_load_lds_dwordx4 v[214:215], off
	v_lshl_add_u64 v[226:227], s[76:77], 0, v[0:1]
	s_mov_b32 m0, s75
	v_lshl_add_u64 v[228:229], s[24:25], 0, v[134:135]
	global_load_lds_dwordx4 v[226:227], off
	v_lshl_add_u64 v[226:227], s[76:77], 0, v[132:133]
	s_add_i32 m0, s75, 0x2000
	s_nop 0
	global_load_lds_dwordx4 v[226:227], off
	v_lshl_add_u64 v[226:227], s[24:25], 0, v[136:137]
	s_mov_b32 m0, s29
	s_nop 0
	global_load_lds_dwordx4 v[226:227], off
	s_mov_b32 m0, s30
	s_nop 0
	global_load_lds_dwordx4 v[228:229], off
	s_waitcnt vmcnt(8)
	s_waitcnt lgkmcnt(0)
	s_barrier
	s_setprio 1
	s_waitcnt lgkmcnt(0)
	v_mfma_f32_16x16x32_bf16 v[62:65], v[148:151], v[180:183], v[62:65]
	v_mfma_f32_16x16x32_bf16 v[58:61], v[156:159], v[180:183], v[58:61]
	v_mfma_f32_16x16x32_bf16 v[50:53], v[148:151], v[188:191], v[50:53]
	v_mfma_f32_16x16x32_bf16 v[42:45], v[156:159], v[188:191], v[42:45]
	v_mfma_f32_16x16x32_bf16 v[34:37], v[148:151], v[196:199], v[34:37]
	v_mfma_f32_16x16x32_bf16 v[26:29], v[156:159], v[196:199], v[26:29]
	v_mfma_f32_16x16x32_bf16 v[18:21], v[148:151], v[204:207], v[18:21]
	v_mfma_f32_16x16x32_bf16 v[10:13], v[156:159], v[204:207], v[10:13]
	v_mfma_f32_16x16x32_bf16 v[62:65], v[152:155], v[184:187], v[62:65]
	v_mfma_f32_16x16x32_bf16 v[58:61], v[160:163], v[184:187], v[58:61]
	v_mfma_f32_16x16x32_bf16 v[50:53], v[152:155], v[192:195], v[50:53]
	v_mfma_f32_16x16x32_bf16 v[42:45], v[160:163], v[192:195], v[42:45]
	v_mfma_f32_16x16x32_bf16 v[34:37], v[152:155], v[200:203], v[34:37]
	v_mfma_f32_16x16x32_bf16 v[26:29], v[160:163], v[200:203], v[26:29]
	v_mfma_f32_16x16x32_bf16 v[18:21], v[152:155], v[218:221], v[18:21]
	v_mfma_f32_16x16x32_bf16 v[10:13], v[160:163], v[218:221], v[10:13]
	s_setprio 0
	s_setprio 1
	v_mfma_f32_16x16x32_bf16 v[54:57], v[164:167], v[180:183], v[54:57]
	v_mfma_f32_16x16x32_bf16 v[46:49], v[172:175], v[180:183], v[46:49]
	v_mfma_f32_16x16x32_bf16 v[38:41], v[164:167], v[188:191], v[38:41]
	v_mfma_f32_16x16x32_bf16 v[30:33], v[172:175], v[188:191], v[30:33]
	v_mfma_f32_16x16x32_bf16 v[22:25], v[164:167], v[196:199], v[22:25]
	v_mfma_f32_16x16x32_bf16 v[14:17], v[172:175], v[196:199], v[14:17]
	v_mfma_f32_16x16x32_bf16 v[6:9], v[164:167], v[204:207], v[6:9]
	v_mfma_f32_16x16x32_bf16 v[2:5], v[172:175], v[204:207], v[2:5]
	v_mfma_f32_16x16x32_bf16 v[54:57], v[168:171], v[184:187], v[54:57]
	v_mfma_f32_16x16x32_bf16 v[46:49], v[176:179], v[184:187], v[46:49]
	v_mfma_f32_16x16x32_bf16 v[38:41], v[168:171], v[192:195], v[38:41]
	v_mfma_f32_16x16x32_bf16 v[30:33], v[176:179], v[192:195], v[30:33]
	v_mfma_f32_16x16x32_bf16 v[22:25], v[168:171], v[200:203], v[22:25]
	v_mfma_f32_16x16x32_bf16 v[14:17], v[176:179], v[200:203], v[14:17]
	v_mfma_f32_16x16x32_bf16 v[6:9], v[168:171], v[218:221], v[6:9]
	v_mfma_f32_16x16x32_bf16 v[2:5], v[176:179], v[218:221], v[2:5]
	s_setprio 0
	s_barrier
	s_add_i32 s75, 0, 0x18000
	v_add_u32_e32 v147, s75, v131
	s_add_i32 s76, 0, 0x1c000
	ds_read_b128 v[148:151], v147
	ds_read_b128 v[152:155], v147 offset:1024
	ds_read_b128 v[156:159], v147 offset:2048
	ds_read_b128 v[160:163], v147 offset:3072
	v_add_u32_e32 v147, s76, v131
	ds_read_b128 v[164:167], v147
	ds_read_b128 v[168:171], v147 offset:1024
	ds_read_b128 v[172:175], v147 offset:2048
	ds_read_b128 v[176:179], v147 offset:3072
	s_add_u32 s24, s24, 0xb0000
	s_addc_u32 s25, s25, 0
	s_mov_b32 m0, s31
	v_lshl_add_u64 v[230:231], s[24:25], 0, v[136:137]
	ds_read_b128 v[180:183], v146 offset:32768
	ds_read_b128 v[184:187], v146 offset:33792
	ds_read_b128 v[188:191], v146 offset:34816
	ds_read_b128 v[192:195], v146 offset:35840
	ds_read_b128 v[196:199], v146 offset:36864
	ds_read_b128 v[200:203], v146 offset:37888
	ds_read_b128 v[204:207], v146 offset:38912
	ds_read_b128 v[218:221], v146 offset:39936
	global_load_lds_dwordx4 v[230:231], off
	v_lshl_add_u64 v[230:231], s[24:25], 0, v[134:135]
	s_mov_b32 m0, s34
	s_nop 0
	global_load_lds_dwordx4 v[230:231], off
	s_waitcnt vmcnt(8)
	s_waitcnt lgkmcnt(0)
	s_barrier
	s_setprio 1
	s_waitcnt lgkmcnt(0)
	v_mfma_f32_16x16x32_bf16 v[126:129], v[148:151], v[180:183], v[126:129]
	v_mfma_f32_16x16x32_bf16 v[122:125], v[156:159], v[180:183], v[122:125]
	v_mfma_f32_16x16x32_bf16 v[114:117], v[148:151], v[188:191], v[114:117]
	v_mfma_f32_16x16x32_bf16 v[106:109], v[156:159], v[188:191], v[106:109]
	v_mfma_f32_16x16x32_bf16 v[98:101], v[148:151], v[196:199], v[98:101]
	v_mfma_f32_16x16x32_bf16 v[90:93], v[156:159], v[196:199], v[90:93]
	v_mfma_f32_16x16x32_bf16 v[82:85], v[148:151], v[204:207], v[82:85]
	v_mfma_f32_16x16x32_bf16 v[74:77], v[156:159], v[204:207], v[74:77]
	v_mfma_f32_16x16x32_bf16 v[126:129], v[152:155], v[184:187], v[126:129]
	v_mfma_f32_16x16x32_bf16 v[122:125], v[160:163], v[184:187], v[122:125]
	v_mfma_f32_16x16x32_bf16 v[114:117], v[152:155], v[192:195], v[114:117]
	v_mfma_f32_16x16x32_bf16 v[106:109], v[160:163], v[192:195], v[106:109]
	v_mfma_f32_16x16x32_bf16 v[98:101], v[152:155], v[200:203], v[98:101]
	v_mfma_f32_16x16x32_bf16 v[90:93], v[160:163], v[200:203], v[90:93]
	v_mfma_f32_16x16x32_bf16 v[82:85], v[152:155], v[218:221], v[82:85]
	v_mfma_f32_16x16x32_bf16 v[74:77], v[160:163], v[218:221], v[74:77]
	s_setprio 0
	s_setprio 1
	v_mfma_f32_16x16x32_bf16 v[118:121], v[164:167], v[180:183], v[118:121]
	v_mfma_f32_16x16x32_bf16 v[110:113], v[172:175], v[180:183], v[110:113]
	v_mfma_f32_16x16x32_bf16 v[102:105], v[164:167], v[188:191], v[102:105]
	v_mfma_f32_16x16x32_bf16 v[94:97], v[172:175], v[188:191], v[94:97]
	v_mfma_f32_16x16x32_bf16 v[86:89], v[164:167], v[196:199], v[86:89]
	v_mfma_f32_16x16x32_bf16 v[78:81], v[172:175], v[196:199], v[78:81]
	v_mfma_f32_16x16x32_bf16 v[70:73], v[164:167], v[204:207], v[70:73]
	v_mfma_f32_16x16x32_bf16 v[66:69], v[172:175], v[204:207], v[66:69]
	v_mfma_f32_16x16x32_bf16 v[118:121], v[168:171], v[184:187], v[118:121]
	v_mfma_f32_16x16x32_bf16 v[110:113], v[176:179], v[184:187], v[110:113]
	v_mfma_f32_16x16x32_bf16 v[102:105], v[168:171], v[192:195], v[102:105]
	v_mfma_f32_16x16x32_bf16 v[94:97], v[176:179], v[192:195], v[94:97]
	v_mfma_f32_16x16x32_bf16 v[86:89], v[168:171], v[200:203], v[86:89]
	v_mfma_f32_16x16x32_bf16 v[78:81], v[176:179], v[200:203], v[78:81]
	v_mfma_f32_16x16x32_bf16 v[70:73], v[168:171], v[218:221], v[70:73]
	v_mfma_f32_16x16x32_bf16 v[66:69], v[176:179], v[218:221], v[66:69]
	s_setprio 0
	s_barrier
	s_add_i32 s24, s75, s28
	v_lshl_add_u64 v[208:209], v[208:209], 0, s[50:51]
	s_mov_b32 m0, s24
	ds_read_b128 v[180:183], v146 offset:49152
	ds_read_b128 v[184:187], v146 offset:50176
	ds_read_b128 v[188:191], v146 offset:51200
	ds_read_b128 v[192:195], v146 offset:52224
	ds_read_b128 v[196:199], v146 offset:53248
	ds_read_b128 v[200:203], v146 offset:54272
	ds_read_b128 v[204:207], v146 offset:55296
	ds_read_b128 v[218:221], v146 offset:56320
	global_load_lds_dwordx4 v[208:209], off
	s_add_i32 m0, s24, 0x2000
	s_add_u32 s22, s22, 0xb0080
	v_lshl_add_u64 v[208:209], v[214:215], 0, s[50:51]
	s_addc_u32 s23, s23, 0
	s_add_i32 s24, s76, s28
	global_load_lds_dwordx4 v[208:209], off
	v_lshl_add_u64 v[208:209], s[22:23], 0, v[0:1]
	s_mov_b32 m0, s24
	s_nop 0
	global_load_lds_dwordx4 v[208:209], off
	v_lshl_add_u64 v[208:209], s[22:23], 0, v[132:133]
	s_add_i32 m0, s24, 0x2000
	s_nop 0
	global_load_lds_dwordx4 v[208:209], off
	v_lshl_add_u64 v[208:209], v[226:227], 0, s[50:51]
	s_mov_b32 m0, s35
	s_nop 0
	global_load_lds_dwordx4 v[208:209], off
	v_lshl_add_u64 v[208:209], v[228:229], 0, s[50:51]
	s_mov_b32 m0, s36
	s_nop 0
	global_load_lds_dwordx4 v[208:209], off
	s_waitcnt vmcnt(8)
	s_waitcnt lgkmcnt(0)
	s_barrier
	s_setprio 1
	s_waitcnt lgkmcnt(0)
	v_mfma_f32_16x16x32_bf16 v[62:65], v[148:151], v[180:183], v[62:65]
	v_mfma_f32_16x16x32_bf16 v[58:61], v[156:159], v[180:183], v[58:61]
	v_mfma_f32_16x16x32_bf16 v[50:53], v[148:151], v[188:191], v[50:53]
	v_mfma_f32_16x16x32_bf16 v[42:45], v[156:159], v[188:191], v[42:45]
	v_mfma_f32_16x16x32_bf16 v[34:37], v[148:151], v[196:199], v[34:37]
	v_mfma_f32_16x16x32_bf16 v[26:29], v[156:159], v[196:199], v[26:29]
	v_mfma_f32_16x16x32_bf16 v[18:21], v[148:151], v[204:207], v[18:21]
	v_mfma_f32_16x16x32_bf16 v[10:13], v[156:159], v[204:207], v[10:13]
	v_mfma_f32_16x16x32_bf16 v[62:65], v[152:155], v[184:187], v[62:65]
	v_mfma_f32_16x16x32_bf16 v[58:61], v[160:163], v[184:187], v[58:61]
	v_mfma_f32_16x16x32_bf16 v[50:53], v[152:155], v[192:195], v[50:53]
	v_mfma_f32_16x16x32_bf16 v[42:45], v[160:163], v[192:195], v[42:45]
	v_mfma_f32_16x16x32_bf16 v[34:37], v[152:155], v[200:203], v[34:37]
	v_mfma_f32_16x16x32_bf16 v[26:29], v[160:163], v[200:203], v[26:29]
	v_mfma_f32_16x16x32_bf16 v[18:21], v[152:155], v[218:221], v[18:21]
	v_mfma_f32_16x16x32_bf16 v[10:13], v[160:163], v[218:221], v[10:13]
	s_setprio 0
	s_setprio 1
	v_mfma_f32_16x16x32_bf16 v[54:57], v[164:167], v[180:183], v[54:57]
	v_mfma_f32_16x16x32_bf16 v[46:49], v[172:175], v[180:183], v[46:49]
	v_mfma_f32_16x16x32_bf16 v[38:41], v[164:167], v[188:191], v[38:41]
	v_mfma_f32_16x16x32_bf16 v[30:33], v[172:175], v[188:191], v[30:33]
	v_mfma_f32_16x16x32_bf16 v[22:25], v[164:167], v[196:199], v[22:25]
	v_mfma_f32_16x16x32_bf16 v[14:17], v[172:175], v[196:199], v[14:17]
	v_mfma_f32_16x16x32_bf16 v[6:9], v[164:167], v[204:207], v[6:9]
	v_mfma_f32_16x16x32_bf16 v[2:5], v[172:175], v[204:207], v[2:5]
	v_mfma_f32_16x16x32_bf16 v[54:57], v[168:171], v[184:187], v[54:57]
	v_mfma_f32_16x16x32_bf16 v[46:49], v[176:179], v[184:187], v[46:49]
	v_mfma_f32_16x16x32_bf16 v[38:41], v[168:171], v[192:195], v[38:41]
	v_mfma_f32_16x16x32_bf16 v[30:33], v[176:179], v[192:195], v[30:33]
	v_mfma_f32_16x16x32_bf16 v[22:25], v[168:171], v[200:203], v[22:25]
	v_mfma_f32_16x16x32_bf16 v[14:17], v[176:179], v[200:203], v[14:17]
	v_mfma_f32_16x16x32_bf16 v[6:9], v[168:171], v[218:221], v[6:9]
	v_mfma_f32_16x16x32_bf16 v[2:5], v[176:179], v[218:221], v[2:5]
	s_setprio 0
	s_barrier
	s_add_i32 s74, s74, 2
	s_add_u32 s20, s20, 0x100
	s_addc_u32 s21, s21, 0
	s_cmp_gt_u32 s74, 41
	s_cbranch_scc0 .LBB0_1226
	s_add_u32 s20, s72, 0xffffff00
	s_addc_u32 s21, s73, -1
	s_and_b64 vcc, exec, s[6:7]
	s_cbranch_vccnz .LBB0_1229
	v_mov_b32_e32 v2, 0
	s_mov_b32 s14, s38
	s_mov_b32 s10, s39
	s_mov_b64 s[16:17], s[18:19]
	s_mov_b32 s37, s71
	v_mov_b32_e32 v3, v2
	v_mov_b64_e32 v[4:5], v[2:3]
	v_mov_b64_e32 v[6:7], v[2:3]
	v_mov_b64_e32 v[8:9], v[2:3]
	v_mov_b64_e32 v[10:11], v[2:3]
	v_mov_b64_e32 v[12:13], v[2:3]
	v_mov_b64_e32 v[14:15], v[2:3]
	v_mov_b64_e32 v[16:17], v[2:3]
	v_mov_b64_e32 v[18:19], v[2:3]
	v_mov_b64_e32 v[20:21], v[2:3]
	v_mov_b64_e32 v[22:23], v[2:3]
	v_mov_b64_e32 v[24:25], v[2:3]
	v_mov_b64_e32 v[26:27], v[2:3]
	v_mov_b64_e32 v[28:29], v[2:3]
	v_mov_b64_e32 v[30:31], v[2:3]
	v_mov_b64_e32 v[32:33], v[2:3]
	v_mov_b64_e32 v[34:35], v[2:3]
	v_mov_b64_e32 v[36:37], v[2:3]
	v_mov_b64_e32 v[38:39], v[2:3]
	v_mov_b64_e32 v[40:41], v[2:3]
	v_mov_b64_e32 v[42:43], v[2:3]
	v_mov_b64_e32 v[44:45], v[2:3]
	v_mov_b64_e32 v[46:47], v[2:3]
	v_mov_b64_e32 v[48:49], v[2:3]
	v_mov_b64_e32 v[50:51], v[2:3]
	v_mov_b64_e32 v[52:53], v[2:3]
	v_mov_b64_e32 v[54:55], v[2:3]
	v_mov_b64_e32 v[56:57], v[2:3]
	v_mov_b64_e32 v[58:59], v[2:3]
	v_mov_b64_e32 v[60:61], v[2:3]
	v_mov_b64_e32 v[62:63], v[2:3]
	v_mov_b64_e32 v[64:65], v[2:3]
	v_mov_b64_e32 v[66:67], v[2:3]
	v_mov_b64_e32 v[68:69], v[2:3]
	v_mov_b64_e32 v[70:71], v[2:3]
	v_mov_b64_e32 v[72:73], v[2:3]
	v_mov_b64_e32 v[74:75], v[2:3]
	v_mov_b64_e32 v[76:77], v[2:3]
	v_mov_b64_e32 v[78:79], v[2:3]
	v_mov_b64_e32 v[80:81], v[2:3]
	v_mov_b64_e32 v[82:83], v[2:3]
	v_mov_b64_e32 v[84:85], v[2:3]
	v_mov_b64_e32 v[86:87], v[2:3]
	v_mov_b64_e32 v[88:89], v[2:3]
	v_mov_b64_e32 v[90:91], v[2:3]
	v_mov_b64_e32 v[92:93], v[2:3]
	v_mov_b64_e32 v[94:95], v[2:3]
	v_mov_b64_e32 v[96:97], v[2:3]
	v_mov_b64_e32 v[98:99], v[2:3]
	v_mov_b64_e32 v[100:101], v[2:3]
	v_mov_b64_e32 v[102:103], v[2:3]
	v_mov_b64_e32 v[104:105], v[2:3]
	v_mov_b64_e32 v[106:107], v[2:3]
	v_mov_b64_e32 v[108:109], v[2:3]
	v_mov_b64_e32 v[110:111], v[2:3]
	v_mov_b64_e32 v[112:113], v[2:3]
	v_mov_b64_e32 v[114:115], v[2:3]
	v_mov_b64_e32 v[116:117], v[2:3]
	v_mov_b64_e32 v[118:119], v[2:3]
	v_mov_b64_e32 v[120:121], v[2:3]
	v_mov_b64_e32 v[122:123], v[2:3]
	v_mov_b64_e32 v[124:125], v[2:3]
	v_mov_b64_e32 v[126:127], v[2:3]
	v_mov_b64_e32 v[128:129], v[2:3]
	s_andn2_b64 vcc, exec, s[4:5]
	s_cbranch_vccnz .LBB0_1230
	s_branch .LBB0_1231
